# hot loop heads (four GEMM K loops, bgemm branch loop) aligned to 64 bytes with s_nop padding
# speedup vs baseline: 1.0051x; 1.0051x over previous
; #define PG8_STAGE(bufoff, gbase, voff) do { _Pragma("unroll") for (int _i = 0; _i < 2; ++_i) \
;         __builtin_amdgcn_global_load_lds((const unsigned*)((const char*)(gbase) + (voff)[_i]), (LAS unsigned*)(lds + (bufoff) + ldsw + _i * 8192), 16, 0, 0); } while (0)
; #define PG8_LDA(dst, b, h) do { _Pragma("unroll") for (int m = 0; m < 4; ++m) _Pragma("unroll") for (int k = 0; k < 2; ++k) dst[m][k] = *(const LAS bf16x8*)(lds + PG8_SA(b, h) + aoff + m * 2048 + k * 1024); } while (0)
; #define PG8_WAIT_V(n) asm volatile("s_waitcnt vmcnt(" #n ")" ::: "memory")
; #define PG8_WAIT_L(n) asm volatile("s_waitcnt lgkmcnt(" #n ")" ::: "memory")
; template <class Epi>
; __device__ __forceinline__ void gemm_phase(LAS unsigned char* lds, const Gemm g, const int G, const int cidx, const Epi& E) {
;     ...
;     const char* cA = PG8_ABASE(cur); const char* cB = (const char*)g.Bt + (size_t)cur.pn * tstep;
;     PG8_STAGE(PG8_SB(0, 0), cB, voffB); PG8_STAGE(PG8_SB(0, 1), cB + hstep, voffB); PG8_STAGE(PG8_SA(0, 0), cA, voffA); PG8_STAGE(PG8_SA(0, 1), cA + hstep, voffA);
;     if (wr == 1) PG8_BAR;
;     PG8_WAIT_V(2); PG8_BAR;
;     PG8_STAGE(PG8_SB(1, 0), cB + kstep, voffB); PG8_STAGE(PG8_SA(1, 0), cA + kstep, voffA); PG8_STAGE(PG8_SB(1, 1), cB + hstep + kstep, voffB);
;     PG8_WAIT_V(6); PG8_BAR;
;     for (;;) {
;         const bool has_next = S.next(ui + 1, nxt);
;         const char* nA = has_next ? PG8_ABASE(nxt) : cA; const char* nB = has_next ? (const char*)g.Bt + (size_t)nxt.pn * tstep : cB;
;         for (int t = 0; t < nt; t += 2) {
;             const bool last = (t == nt - 2);
;             const char* a1 = cA + (size_t)(t + 1) * kstep;
;             const char* a2 = last ? nA : cA + (size_t)(t + 2) * kstep; const char* b2 = last ? nB : cB + (size_t)(t + 2) * kstep;
;             const char* a3 = a2 + kstep; const char* b3 = b2 + kstep;
;             PG8_LDB(B0, 0, 0); PG8_LDB(B1, 0, 1); PG8_SCHED; PG8_LDA(At, 0, 0); PG8_STAGE(PG8_SA(1, 1), a1 + hstep, voffA);
;             PG8_WAIT_V(8); PG8_WAIT_L(0); PG8_BAR; PG8_MMA(0, 0, At, B0); PG8_MMA(0, 1, At, B1); PG8_BAR; PG8_SCHED;
;             PG8_LDA(At, 0, 1); PG8_STAGE(PG8_SB(0, 0), b2, voffB); PG8_STAGE(PG8_SB(0, 1), b2 + hstep, voffB); PG8_STAGE(PG8_SA(0, 0), a2, voffA);
;             PG8_WAIT_V(8); PG8_WAIT_L(0); PG8_BAR; PG8_MMA(1, 0, At, B0); PG8_MMA(1, 1, At, B1); PG8_BAR; PG8_SCHED;
.LBB0_81:
	s_ashr_i32 s13, s12, 31
	v_cmp_lt_i64_e32 vcc, s[14:15], v[240:241]
	s_lshl_b64 s[14:15], s[12:13], 19
	s_add_u32 s14, s42, s14
	s_addc_u32 s15, s94, s15
	s_and_b64 s[18:19], vcc, exec
	s_cselect_b32 s13, s15, s27
	s_cselect_b32 s17, s14, s26
	s_ashr_i32 s9, s8, 31
	s_lshl_b64 s[18:19], s[8:9], 19
	s_add_u32 s18, s96, s18
	s_addc_u32 s19, s97, s19
	s_and_b64 s[28:29], vcc, exec
	s_cselect_b32 s9, s19, s25
	s_cselect_b32 s22, s18, s24
	s_add_u32 s33, s24, 0x100
	s_addc_u32 s44, s25, 0
	s_add_u32 s24, s26, 0x40080
	s_addc_u32 s25, s27, 0
	s_mov_b32 s45, -2
	s_add_u32 s26, s24, 0xfffc0080
	s_addc_u32 s27, s25, -1
	s_add_i32 s43, 0, 0x10000
	s_cmp_eq_u32 s45, 12
	s_cselect_b32 s29, s13, s27
	s_cselect_b32 s28, s17, s26
	s_cselect_b32 s27, s9, s44
	s_cselect_b32 s26, s22, s33
	s_add_i32 s68, 0, 0x14000
	v_add_u32_e32 v162, s43, v145
	v_add_u32_e32 v178, s68, v145
	ds_read_b128 v[132:135], v162
	ds_read_b128 v[140:143], v162 offset:1024
	ds_read_b128 v[156:159], v162 offset:2048
	ds_read_b128 v[162:165], v162 offset:3072
	ds_read_b128 v[166:169], v178
	ds_read_b128 v[170:173], v178 offset:1024
	ds_read_b128 v[174:177], v178 offset:2048
	ds_read_b128 v[178:181], v178 offset:3072
	v_lshl_add_u64 v[226:227], s[24:25], 0, v[154:155]
	s_add_i32 m0, s21, 0xc000
	ds_read_b128 v[182:185], v161
	ds_read_b128 v[186:189], v161 offset:1024
	ds_read_b128 v[190:193], v161 offset:2048
	ds_read_b128 v[194:197], v161 offset:3072
	ds_read_b128 v[198:201], v161 offset:4096
	ds_read_b128 v[214:217], v161 offset:5120
	ds_read_b128 v[218:221], v161 offset:6144
	ds_read_b128 v[222:225], v161 offset:7168
	global_load_lds_dwordx4 v[226:227], off
	v_lshl_add_u64 v[226:227], s[24:25], 0, v[152:153]
	s_add_i32 m0, s21, 0xe000
	s_nop 0
	global_load_lds_dwordx4 v[226:227], off
	s_waitcnt vmcnt(8)
	s_waitcnt lgkmcnt(0)
	s_barrier
	s_setprio 1
	s_waitcnt lgkmcnt(0)
	v_mfma_f32_16x16x32_bf16 v[128:131], v[132:135], v[182:185], 0
	v_mfma_f32_16x16x32_bf16 v[120:123], v[156:159], v[182:185], 0
	v_mfma_f32_16x16x32_bf16 v[112:115], v[132:135], v[190:193], 0
	v_mfma_f32_16x16x32_bf16 v[104:107], v[156:159], v[190:193], 0
	v_mfma_f32_16x16x32_bf16 v[96:99], v[132:135], v[198:201], 0
	v_mfma_f32_16x16x32_bf16 v[88:91], v[156:159], v[198:201], 0
	v_mfma_f32_16x16x32_bf16 v[80:83], v[132:135], v[218:221], 0
	v_mfma_f32_16x16x32_bf16 v[72:75], v[156:159], v[218:221], 0
	v_mfma_f32_16x16x32_bf16 v[128:131], v[140:143], v[186:189], v[128:131]
	v_mfma_f32_16x16x32_bf16 v[120:123], v[162:165], v[186:189], v[120:123]
	v_mfma_f32_16x16x32_bf16 v[112:115], v[140:143], v[194:197], v[112:115]
	v_mfma_f32_16x16x32_bf16 v[104:107], v[162:165], v[194:197], v[104:107]
	v_mfma_f32_16x16x32_bf16 v[96:99], v[140:143], v[214:217], v[96:99]
	v_mfma_f32_16x16x32_bf16 v[88:91], v[162:165], v[214:217], v[88:91]
	v_mfma_f32_16x16x32_bf16 v[80:83], v[140:143], v[222:225], v[80:83]
	v_mfma_f32_16x16x32_bf16 v[72:75], v[162:165], v[222:225], v[72:75]
	s_setprio 0
	s_setprio 1
	v_mfma_f32_16x16x32_bf16 v[124:127], v[166:169], v[182:185], 0
	v_mfma_f32_16x16x32_bf16 v[116:119], v[174:177], v[182:185], 0
	v_mfma_f32_16x16x32_bf16 v[108:111], v[166:169], v[190:193], 0
	v_mfma_f32_16x16x32_bf16 v[100:103], v[174:177], v[190:193], 0
	v_mfma_f32_16x16x32_bf16 v[92:95], v[166:169], v[198:201], 0
	v_mfma_f32_16x16x32_bf16 v[84:87], v[174:177], v[198:201], 0
	v_mfma_f32_16x16x32_bf16 v[76:79], v[166:169], v[218:221], 0
	v_mfma_f32_16x16x32_bf16 v[68:71], v[174:177], v[218:221], 0
	v_mfma_f32_16x16x32_bf16 v[124:127], v[170:173], v[186:189], v[124:127]
	v_mfma_f32_16x16x32_bf16 v[116:119], v[178:181], v[186:189], v[116:119]
	v_mfma_f32_16x16x32_bf16 v[108:111], v[170:173], v[194:197], v[108:111]
	v_mfma_f32_16x16x32_bf16 v[100:103], v[178:181], v[194:197], v[100:103]
	v_mfma_f32_16x16x32_bf16 v[92:95], v[170:173], v[214:217], v[92:95]
	v_mfma_f32_16x16x32_bf16 v[84:87], v[178:181], v[214:217], v[84:87]
	v_mfma_f32_16x16x32_bf16 v[76:79], v[170:173], v[222:225], v[76:79]
	v_mfma_f32_16x16x32_bf16 v[68:71], v[178:181], v[222:225], v[68:71]
	s_setprio 0
	s_barrier
	s_add_i32 s43, s43, s36
	v_lshl_add_u64 v[226:227], s[26:27], 0, v[148:149]
	s_mov_b32 m0, s43
	ds_read_b128 v[182:185], v161 offset:16384
	ds_read_b128 v[186:189], v161 offset:17408
	ds_read_b128 v[190:193], v161 offset:18432
	ds_read_b128 v[194:197], v161 offset:19456
	ds_read_b128 v[198:201], v161 offset:20480
	ds_read_b128 v[214:217], v161 offset:21504
	ds_read_b128 v[218:221], v161 offset:22528
	ds_read_b128 v[222:225], v161 offset:23552
	global_load_lds_dwordx4 v[226:227], off
	s_add_i32 m0, s43, 0x2000
	s_add_u32 s76, s26, 0x40000
	v_lshl_add_u64 v[228:229], s[26:27], 0, v[0:1]
	s_addc_u32 s77, s27, 0
	s_add_i32 s43, s68, s36
	global_load_lds_dwordx4 v[228:229], off
	v_lshl_add_u64 v[230:231], s[76:77], 0, v[148:149]
	s_mov_b32 m0, s43
	v_lshl_add_u64 v[232:233], s[28:29], 0, v[146:147]
	global_load_lds_dwordx4 v[230:231], off
	v_lshl_add_u64 v[230:231], s[76:77], 0, v[0:1]
	s_add_i32 m0, s43, 0x2000
	s_nop 0
	global_load_lds_dwordx4 v[230:231], off
	v_lshl_add_u64 v[230:231], s[28:29], 0, v[150:151]
	s_mov_b32 m0, s21
	s_nop 0
	global_load_lds_dwordx4 v[230:231], off
	s_mov_b32 m0, s38
	s_nop 0
	global_load_lds_dwordx4 v[232:233], off
	s_waitcnt vmcnt(8)
	s_waitcnt lgkmcnt(0)
	s_barrier
; #define PG8_STAGE(bufoff, gbase, voff) do { _Pragma("unroll") for (int _i = 0; _i < 2; ++_i) \
;         __builtin_amdgcn_global_load_lds((const unsigned*)((const char*)(gbase) + (voff)[_i]), (LAS unsigned*)(lds + (bufoff) + ldsw + _i * 8192), 16, 0, 0); } while (0)
; #define PG8_LDA(dst, b, h) do { _Pragma("unroll") for (int m = 0; m < 4; ++m) _Pragma("unroll") for (int k = 0; k < 2; ++k) dst[m][k] = *(const LAS bf16x8*)(lds + PG8_SA(b, h) + aoff + m * 2048 + k * 1024); } while (0)
; #define PG8_LDB(dst, b, h) do { _Pragma("unroll") for (int n = 0; n < 2; ++n) _Pragma("unroll") for (int k = 0; k < 2; ++k) dst[n][k] = *(const LAS bf16x8*)(lds + PG8_SB(b, h) + boff + n * 2048 + k * 1024); } while (0)
; #define PG8_MMA(ai, bj, At, Bt) do { __builtin_amdgcn_s_setprio(1); _Pragma("unroll") for (int m = 0; m < 4; ++m) _Pragma("unroll") for (int n = 0; n < 2; ++n) _Pragma("unroll") for (int k = 0; k < 2; ++k) \
;         acc[ai][bj][m][n] = __builtin_amdgcn_mfma_f32_16x16x32_bf16(Bt[n][k], At[m][k], acc[ai][bj][m][n], 0, 0, 0); __builtin_amdgcn_s_setprio(0); } while (0)
; #define PG8_WAIT_V(n) asm volatile("s_waitcnt vmcnt(" #n ")" ::: "memory")
; #define PG8_WAIT_L(n) asm volatile("s_waitcnt lgkmcnt(" #n ")" ::: "memory")
; #define PG8_BAR __builtin_amdgcn_s_barrier()
; #define PG8_SCHED __builtin_amdgcn_sched_barrier(0)
; template <class Epi>
; __device__ __forceinline__ void gemm_phase(LAS unsigned char* lds, const Gemm g, const int G, const int cidx, const Epi& E) {
;     ...
;             PG8_WAIT_V(8); PG8_WAIT_L(0); PG8_BAR; PG8_MMA(1, 0, At, B0); PG8_MMA(1, 1, At, B1); PG8_BAR; PG8_SCHED;
;             PG8_LDB(B0, 1, 0); PG8_LDB(B1, 1, 1); PG8_SCHED; PG8_LDA(At, 1, 0); PG8_STAGE(PG8_SA(0, 1), a2 + hstep, voffA);
;             PG8_WAIT_V(8); PG8_WAIT_L(0); PG8_BAR; PG8_MMA(0, 0, At, B0); PG8_MMA(0, 1, At, B1); PG8_BAR; PG8_SCHED;
	s_setprio 1
	s_waitcnt lgkmcnt(0)
	v_mfma_f32_16x16x32_bf16 v[64:67], v[132:135], v[182:185], 0
	v_mfma_f32_16x16x32_bf16 v[56:59], v[156:159], v[182:185], 0
	v_mfma_f32_16x16x32_bf16 v[48:51], v[132:135], v[190:193], 0
	v_mfma_f32_16x16x32_bf16 v[40:43], v[156:159], v[190:193], 0
	v_mfma_f32_16x16x32_bf16 v[32:35], v[132:135], v[198:201], 0
	v_mfma_f32_16x16x32_bf16 v[24:27], v[156:159], v[198:201], 0
	v_mfma_f32_16x16x32_bf16 v[16:19], v[132:135], v[218:221], 0
	v_mfma_f32_16x16x32_bf16 v[8:11], v[156:159], v[218:221], 0
	v_mfma_f32_16x16x32_bf16 v[64:67], v[140:143], v[186:189], v[64:67]
	v_mfma_f32_16x16x32_bf16 v[56:59], v[162:165], v[186:189], v[56:59]
	v_mfma_f32_16x16x32_bf16 v[48:51], v[140:143], v[194:197], v[48:51]
	v_mfma_f32_16x16x32_bf16 v[40:43], v[162:165], v[194:197], v[40:43]
	v_mfma_f32_16x16x32_bf16 v[32:35], v[140:143], v[214:217], v[32:35]
	v_mfma_f32_16x16x32_bf16 v[24:27], v[162:165], v[214:217], v[24:27]
	v_mfma_f32_16x16x32_bf16 v[16:19], v[140:143], v[222:225], v[16:19]
	v_mfma_f32_16x16x32_bf16 v[8:11], v[162:165], v[222:225], v[8:11]
	s_setprio 0
	s_setprio 1
	v_mfma_f32_16x16x32_bf16 v[60:63], v[166:169], v[182:185], 0
	v_mfma_f32_16x16x32_bf16 v[52:55], v[174:177], v[182:185], 0
	v_mfma_f32_16x16x32_bf16 v[44:47], v[166:169], v[190:193], 0
	v_mfma_f32_16x16x32_bf16 v[36:39], v[174:177], v[190:193], 0
	v_mfma_f32_16x16x32_bf16 v[28:31], v[166:169], v[198:201], 0
	v_mfma_f32_16x16x32_bf16 v[20:23], v[174:177], v[198:201], 0
	v_mfma_f32_16x16x32_bf16 v[12:15], v[166:169], v[218:221], 0
	v_mfma_f32_16x16x32_bf16 v[4:7], v[174:177], v[218:221], 0
	v_mfma_f32_16x16x32_bf16 v[60:63], v[170:173], v[186:189], v[60:63]
	v_mfma_f32_16x16x32_bf16 v[52:55], v[178:181], v[186:189], v[52:55]
	v_mfma_f32_16x16x32_bf16 v[44:47], v[170:173], v[194:197], v[44:47]
	v_mfma_f32_16x16x32_bf16 v[36:39], v[178:181], v[194:197], v[36:39]
	v_mfma_f32_16x16x32_bf16 v[28:31], v[170:173], v[214:217], v[28:31]
	v_mfma_f32_16x16x32_bf16 v[20:23], v[178:181], v[214:217], v[20:23]
	v_mfma_f32_16x16x32_bf16 v[12:15], v[170:173], v[222:225], v[12:15]
	v_mfma_f32_16x16x32_bf16 v[4:7], v[178:181], v[222:225], v[4:7]
	s_setprio 0
	s_barrier
	s_add_i32 s43, 0, 0x18000
	s_add_i32 s68, 0, 0x1c000
	v_add_u32_e32 v162, s43, v145
	v_add_u32_e32 v178, s68, v145
	ds_read_b128 v[132:135], v162
	ds_read_b128 v[140:143], v162 offset:1024
	ds_read_b128 v[156:159], v162 offset:2048
	ds_read_b128 v[162:165], v162 offset:3072
	ds_read_b128 v[166:169], v178
	ds_read_b128 v[170:173], v178 offset:1024
	ds_read_b128 v[174:177], v178 offset:2048
	ds_read_b128 v[178:181], v178 offset:3072
	s_add_u32 s28, s28, 0x40000
	s_addc_u32 s29, s29, 0
	s_mov_b32 m0, s39
	v_lshl_add_u64 v[234:235], s[28:29], 0, v[150:151]
	ds_read_b128 v[182:185], v161 offset:32768
	ds_read_b128 v[186:189], v161 offset:33792
	ds_read_b128 v[190:193], v161 offset:34816
	ds_read_b128 v[194:197], v161 offset:35840
	ds_read_b128 v[198:201], v161 offset:36864
	ds_read_b128 v[214:217], v161 offset:37888
	ds_read_b128 v[218:221], v161 offset:38912
	ds_read_b128 v[222:225], v161 offset:39936
	global_load_lds_dwordx4 v[234:235], off
	v_lshl_add_u64 v[234:235], s[28:29], 0, v[146:147]
	s_mov_b32 m0, s75
	s_nop 0
	global_load_lds_dwordx4 v[234:235], off
	s_waitcnt vmcnt(8)
	s_waitcnt lgkmcnt(0)
	s_barrier
	s_setprio 1
	s_waitcnt lgkmcnt(0)
	v_mfma_f32_16x16x32_bf16 v[128:131], v[132:135], v[182:185], v[128:131]
	v_mfma_f32_16x16x32_bf16 v[120:123], v[156:159], v[182:185], v[120:123]
	v_mfma_f32_16x16x32_bf16 v[112:115], v[132:135], v[190:193], v[112:115]
	v_mfma_f32_16x16x32_bf16 v[104:107], v[156:159], v[190:193], v[104:107]
	v_mfma_f32_16x16x32_bf16 v[96:99], v[132:135], v[198:201], v[96:99]
	v_mfma_f32_16x16x32_bf16 v[88:91], v[156:159], v[198:201], v[88:91]
	v_mfma_f32_16x16x32_bf16 v[80:83], v[132:135], v[218:221], v[80:83]
	v_mfma_f32_16x16x32_bf16 v[72:75], v[156:159], v[218:221], v[72:75]
	v_mfma_f32_16x16x32_bf16 v[128:131], v[140:143], v[186:189], v[128:131]
	v_mfma_f32_16x16x32_bf16 v[120:123], v[162:165], v[186:189], v[120:123]
	v_mfma_f32_16x16x32_bf16 v[112:115], v[140:143], v[194:197], v[112:115]
	v_mfma_f32_16x16x32_bf16 v[104:107], v[162:165], v[194:197], v[104:107]
	v_mfma_f32_16x16x32_bf16 v[96:99], v[140:143], v[214:217], v[96:99]
	v_mfma_f32_16x16x32_bf16 v[88:91], v[162:165], v[214:217], v[88:91]
	v_mfma_f32_16x16x32_bf16 v[80:83], v[140:143], v[222:225], v[80:83]
	v_mfma_f32_16x16x32_bf16 v[72:75], v[162:165], v[222:225], v[72:75]
	s_setprio 0
	s_setprio 1
	v_mfma_f32_16x16x32_bf16 v[124:127], v[166:169], v[182:185], v[124:127]
	v_mfma_f32_16x16x32_bf16 v[116:119], v[174:177], v[182:185], v[116:119]
	v_mfma_f32_16x16x32_bf16 v[108:111], v[166:169], v[190:193], v[108:111]
	v_mfma_f32_16x16x32_bf16 v[100:103], v[174:177], v[190:193], v[100:103]
	v_mfma_f32_16x16x32_bf16 v[92:95], v[166:169], v[198:201], v[92:95]
	v_mfma_f32_16x16x32_bf16 v[84:87], v[174:177], v[198:201], v[84:87]
	v_mfma_f32_16x16x32_bf16 v[76:79], v[166:169], v[218:221], v[76:79]
	v_mfma_f32_16x16x32_bf16 v[68:71], v[174:177], v[218:221], v[68:71]
	v_mfma_f32_16x16x32_bf16 v[124:127], v[170:173], v[186:189], v[124:127]
	v_mfma_f32_16x16x32_bf16 v[116:119], v[178:181], v[186:189], v[116:119]
	v_mfma_f32_16x16x32_bf16 v[108:111], v[170:173], v[194:197], v[108:111]
	v_mfma_f32_16x16x32_bf16 v[100:103], v[178:181], v[194:197], v[100:103]
	v_mfma_f32_16x16x32_bf16 v[92:95], v[170:173], v[214:217], v[92:95]
	v_mfma_f32_16x16x32_bf16 v[84:87], v[178:181], v[214:217], v[84:87]
	v_mfma_f32_16x16x32_bf16 v[76:79], v[170:173], v[222:225], v[76:79]
	v_mfma_f32_16x16x32_bf16 v[68:71], v[178:181], v[222:225], v[68:71]
	s_setprio 0
	s_barrier
; #define PG8_STAGE(bufoff, gbase, voff) do { _Pragma("unroll") for (int _i = 0; _i < 2; ++_i) \
;         __builtin_amdgcn_global_load_lds((const unsigned*)((const char*)(gbase) + (voff)[_i]), (LAS unsigned*)(lds + (bufoff) + ldsw + _i * 8192), 16, 0, 0); } while (0)
; #define PG8_LDA(dst, b, h) do { _Pragma("unroll") for (int m = 0; m < 4; ++m) _Pragma("unroll") for (int k = 0; k < 2; ++k) dst[m][k] = *(const LAS bf16x8*)(lds + PG8_SA(b, h) + aoff + m * 2048 + k * 1024); } while (0)
; #define PG8_MMA(ai, bj, At, Bt) do { __builtin_amdgcn_s_setprio(1); _Pragma("unroll") for (int m = 0; m < 4; ++m) _Pragma("unroll") for (int n = 0; n < 2; ++n) _Pragma("unroll") for (int k = 0; k < 2; ++k) \
;         acc[ai][bj][m][n] = __builtin_amdgcn_mfma_f32_16x16x32_bf16(Bt[n][k], At[m][k], acc[ai][bj][m][n], 0, 0, 0); __builtin_amdgcn_s_setprio(0); } while (0)
; #define PG8_WAIT_V(n) asm volatile("s_waitcnt vmcnt(" #n ")" ::: "memory")
; #define PG8_WAIT_L(n) asm volatile("s_waitcnt lgkmcnt(" #n ")" ::: "memory")
; #define PG8_BAR __builtin_amdgcn_s_barrier()
; #define PG8_SCHED __builtin_amdgcn_sched_barrier(0)
; template <class Epi>
; __device__ __forceinline__ void gemm_phase(LAS unsigned char* lds, const Gemm g, const int G, const int cidx, const Epi& E) {
;     ...
;             PG8_LDA(At, 1, 1); PG8_STAGE(PG8_SB(1, 0), b3, voffB); PG8_STAGE(PG8_SB(1, 1), b3 + hstep, voffB); PG8_STAGE(PG8_SA(1, 0), a3, voffA);
;             PG8_WAIT_V(8); PG8_WAIT_L(0); PG8_BAR; PG8_MMA(1, 0, At, B0); PG8_MMA(1, 1, At, B1); PG8_BAR; PG8_SCHED;
;         }
	s_add_i32 s28, s43, s36
	v_lshl_add_u64 v[226:227], v[226:227], 0, s[46:47]
	s_mov_b32 m0, s28
	ds_read_b128 v[182:185], v161 offset:49152
	ds_read_b128 v[186:189], v161 offset:50176
	ds_read_b128 v[190:193], v161 offset:51200
	ds_read_b128 v[194:197], v161 offset:52224
	ds_read_b128 v[198:201], v161 offset:53248
	ds_read_b128 v[214:217], v161 offset:54272
	ds_read_b128 v[218:221], v161 offset:55296
	ds_read_b128 v[222:225], v161 offset:56320
	global_load_lds_dwordx4 v[226:227], off
	s_add_i32 m0, s28, 0x2000
	s_add_u32 s26, s26, 0x40080
	v_lshl_add_u64 v[226:227], v[228:229], 0, s[46:47]
	s_addc_u32 s27, s27, 0
	s_add_i32 s28, s68, s36
	global_load_lds_dwordx4 v[226:227], off
	v_lshl_add_u64 v[226:227], s[26:27], 0, v[148:149]
	s_mov_b32 m0, s28
	s_nop 0
	global_load_lds_dwordx4 v[226:227], off
	v_lshl_add_u64 v[226:227], s[26:27], 0, v[0:1]
	s_add_i32 m0, s28, 0x2000
	s_nop 0
	global_load_lds_dwordx4 v[226:227], off
	v_lshl_add_u64 v[226:227], v[230:231], 0, s[46:47]
	s_mov_b32 m0, s79
	s_nop 0
	global_load_lds_dwordx4 v[226:227], off
	v_lshl_add_u64 v[226:227], v[232:233], 0, s[46:47]
	s_mov_b32 m0, s34
	s_nop 0
	global_load_lds_dwordx4 v[226:227], off
	s_waitcnt vmcnt(8)
	s_waitcnt lgkmcnt(0)
	s_barrier
	s_setprio 1
	s_waitcnt lgkmcnt(0)
	v_mfma_f32_16x16x32_bf16 v[64:67], v[132:135], v[182:185], v[64:67]
	v_mfma_f32_16x16x32_bf16 v[56:59], v[156:159], v[182:185], v[56:59]
	v_mfma_f32_16x16x32_bf16 v[48:51], v[132:135], v[190:193], v[48:51]
	v_mfma_f32_16x16x32_bf16 v[40:43], v[156:159], v[190:193], v[40:43]
	v_mfma_f32_16x16x32_bf16 v[32:35], v[132:135], v[198:201], v[32:35]
	v_mfma_f32_16x16x32_bf16 v[24:27], v[156:159], v[198:201], v[24:27]
	v_mfma_f32_16x16x32_bf16 v[16:19], v[132:135], v[218:221], v[16:19]
	v_mfma_f32_16x16x32_bf16 v[8:11], v[156:159], v[218:221], v[8:11]
	v_mfma_f32_16x16x32_bf16 v[64:67], v[140:143], v[186:189], v[64:67]
	v_mfma_f32_16x16x32_bf16 v[56:59], v[162:165], v[186:189], v[56:59]
	v_mfma_f32_16x16x32_bf16 v[48:51], v[140:143], v[194:197], v[48:51]
	v_mfma_f32_16x16x32_bf16 v[40:43], v[162:165], v[194:197], v[40:43]
	v_mfma_f32_16x16x32_bf16 v[32:35], v[140:143], v[214:217], v[32:35]
	v_mfma_f32_16x16x32_bf16 v[24:27], v[162:165], v[214:217], v[24:27]
	v_mfma_f32_16x16x32_bf16 v[16:19], v[140:143], v[222:225], v[16:19]
	v_mfma_f32_16x16x32_bf16 v[8:11], v[162:165], v[222:225], v[8:11]
	s_setprio 0
	s_setprio 1
	v_mfma_f32_16x16x32_bf16 v[60:63], v[166:169], v[182:185], v[60:63]
	v_mfma_f32_16x16x32_bf16 v[52:55], v[174:177], v[182:185], v[52:55]
	v_mfma_f32_16x16x32_bf16 v[44:47], v[166:169], v[190:193], v[44:47]
	v_mfma_f32_16x16x32_bf16 v[36:39], v[174:177], v[190:193], v[36:39]
	v_mfma_f32_16x16x32_bf16 v[28:31], v[166:169], v[198:201], v[28:31]
	v_mfma_f32_16x16x32_bf16 v[20:23], v[174:177], v[198:201], v[20:23]
	v_mfma_f32_16x16x32_bf16 v[12:15], v[166:169], v[218:221], v[12:15]
	v_mfma_f32_16x16x32_bf16 v[4:7], v[174:177], v[218:221], v[4:7]
	v_mfma_f32_16x16x32_bf16 v[60:63], v[170:173], v[186:189], v[60:63]
	v_mfma_f32_16x16x32_bf16 v[52:55], v[178:181], v[186:189], v[52:55]
	v_mfma_f32_16x16x32_bf16 v[44:47], v[170:173], v[194:197], v[44:47]
	v_mfma_f32_16x16x32_bf16 v[36:39], v[178:181], v[194:197], v[36:39]
	v_mfma_f32_16x16x32_bf16 v[28:31], v[170:173], v[214:217], v[28:31]
	v_mfma_f32_16x16x32_bf16 v[20:23], v[178:181], v[214:217], v[20:23]
	v_mfma_f32_16x16x32_bf16 v[12:15], v[170:173], v[222:225], v[12:15]
	v_mfma_f32_16x16x32_bf16 v[4:7], v[178:181], v[222:225], v[4:7]
	s_setprio 0
	s_barrier
	s_add_i32 s45, s45, 2
	s_add_u32 s33, s33, 0x100
	s_addc_u32 s44, s44, 0
	s_add_u32 s24, s24, 0x100
	s_addc_u32 s25, s25, 0
	.p2alignl 6, 3212836864

; #define PG8_STAGE(bufoff, gbase, voff) do { _Pragma("unroll") for (int _i = 0; _i < 2; ++_i) \
;         __builtin_amdgcn_global_load_lds((const unsigned*)((const char*)(gbase) + (voff)[_i]), (LAS unsigned*)(lds + (bufoff) + ldsw + _i * 8192), 16, 0, 0); } while (0)
; #define PG8_LDA(dst, b, h) do { _Pragma("unroll") for (int m = 0; m < 4; ++m) _Pragma("unroll") for (int k = 0; k < 2; ++k) dst[m][k] = *(const LAS bf16x8*)(lds + PG8_SA(b, h) + aoff + m * 2048 + k * 1024); } while (0)
; #define PG8_LDB(dst, b, h) do { _Pragma("unroll") for (int n = 0; n < 2; ++n) _Pragma("unroll") for (int k = 0; k < 2; ++k) dst[n][k] = *(const LAS bf16x8*)(lds + PG8_SB(b, h) + boff + n * 2048 + k * 1024); } while (0)
; #define PG8_MMA(ai, bj, At, Bt) do { __builtin_amdgcn_s_setprio(1); _Pragma("unroll") for (int m = 0; m < 4; ++m) _Pragma("unroll") for (int n = 0; n < 2; ++n) _Pragma("unroll") for (int k = 0; k < 2; ++k) \
;         acc[ai][bj][m][n] = __builtin_amdgcn_mfma_f32_16x16x32_bf16(Bt[n][k], At[m][k], acc[ai][bj][m][n], 0, 0, 0); __builtin_amdgcn_s_setprio(0); } while (0)
; #define PG8_WAIT_V(n) asm volatile("s_waitcnt vmcnt(" #n ")" ::: "memory")
; #define PG8_WAIT_L(n) asm volatile("s_waitcnt lgkmcnt(" #n ")" ::: "memory")
; template <class Epi>
; __device__ __forceinline__ void gemm_phase(LAS unsigned char* lds, const Gemm g, const int G, const int cidx, const Epi& E) {
;     ...
;         const char* nA = has_next ? PG8_ABASE(nxt) : cA; const char* nB = has_next ? (const char*)g.Bt + (size_t)nxt.pn * tstep : cB;
;         for (int t = 0; t < nt; t += 2) {
;             const bool last = (t == nt - 2);
;             const char* a1 = cA + (size_t)(t + 1) * kstep;
;             const char* a2 = last ? nA : cA + (size_t)(t + 2) * kstep; const char* b2 = last ? nB : cB + (size_t)(t + 2) * kstep;
;             const char* a3 = a2 + kstep; const char* b3 = b2 + kstep;
;             PG8_LDB(B0, 0, 0); PG8_LDB(B1, 0, 1); PG8_SCHED; PG8_LDA(At, 0, 0); PG8_STAGE(PG8_SA(1, 1), a1 + hstep, voffA);
;             PG8_WAIT_V(8); PG8_WAIT_L(0); PG8_BAR; PG8_MMA(0, 0, At, B0); PG8_MMA(0, 1, At, B1); PG8_BAR; PG8_SCHED;
;             PG8_LDA(At, 0, 1); PG8_STAGE(PG8_SB(0, 0), b2, voffB); PG8_STAGE(PG8_SB(0, 1), b2 + hstep, voffB); PG8_STAGE(PG8_SA(0, 0), a2, voffA);
;             PG8_WAIT_V(8); PG8_WAIT_L(0); PG8_BAR; PG8_MMA(1, 0, At, B0); PG8_MMA(1, 1, At, B1); PG8_BAR; PG8_SCHED;
.LBB0_215:
	s_add_u32 s43, s70, 0x100
	s_addc_u32 s44, s71, 0
	s_ashr_i32 s31, s30, 31
	s_lshl_b64 s[34:35], s[30:31], 19
	s_add_u32 s36, s12, s34
	s_addc_u32 s37, s13, s35
	s_and_b64 s[34:35], s[6:7], exec
	s_cselect_b32 s31, s37, s9
	s_cselect_b32 s45, s36, s8
	s_ashr_i32 s29, s28, 31
	s_lshl_b64 s[34:35], s[28:29], 19
	s_add_u32 s34, s17, s34
	s_addc_u32 s35, s22, s35
	s_and_b64 s[72:73], s[6:7], exec
	s_cselect_b32 s29, s35, s71
	s_cselect_b32 s68, s34, s70
	s_add_u32 s70, s8, 0x40080
	s_addc_u32 s71, s9, 0
	v_lshl_add_u64 v[0:1], s[70:71], 0, v[150:151]
	v_lshl_add_u64 v[154:155], s[70:71], 0, v[152:153]
	s_mov_b32 s77, -2
	s_mov_b64 s[70:71], 0
	s_add_u32 s72, s8, s70
	s_addc_u32 s73, s9, s71
	s_add_u32 s72, s72, 0x100
	s_addc_u32 s73, s73, 0
	s_add_u32 s83, s43, s70
	s_addc_u32 s86, s44, s71
	s_add_i32 s87, 0, 0x10000
	s_cmpk_eq_i32 s70, 0x700
	s_cselect_b32 s75, s31, s73
	s_cselect_b32 s74, s45, s72
	v_add_u32_e32 v3, s87, v158
	s_cselect_b32 s73, s29, s86
	s_cselect_b32 s72, s68, s83
	s_add_i32 s83, 0, 0x14000
	ds_read_b128 v[132:135], v3
	ds_read_b128 v[140:143], v3 offset:1024
	ds_read_b128 v[160:163], v3 offset:2048
	ds_read_b128 v[164:167], v3 offset:3072
	v_add_u32_e32 v3, s83, v158
	ds_read_b128 v[168:171], v3
	ds_read_b128 v[172:175], v3 offset:1024
	ds_read_b128 v[176:179], v3 offset:2048
	ds_read_b128 v[180:183], v3 offset:3072
	v_lshl_add_u64 v[200:201], v[154:155], 0, s[70:71]
	s_add_i32 m0, s19, 0xc000
	ds_read_b128 v[184:187], v159
	ds_read_b128 v[188:191], v159 offset:1024
	ds_read_b128 v[192:195], v159 offset:2048
	ds_read_b128 v[196:199], v159 offset:3072
	ds_read_b128 v[214:217], v159 offset:4096
	ds_read_b128 v[218:221], v159 offset:5120
	ds_read_b128 v[222:225], v159 offset:6144
	ds_read_b128 v[226:229], v159 offset:7168
	global_load_lds_dwordx4 v[200:201], off
	v_lshl_add_u64 v[200:201], v[0:1], 0, s[70:71]
	s_add_i32 m0, s19, 0xe000
	s_nop 0
	global_load_lds_dwordx4 v[200:201], off
	s_waitcnt vmcnt(8)
	s_waitcnt lgkmcnt(0)
	s_barrier
	s_setprio 1
	s_waitcnt lgkmcnt(0)
	v_mfma_f32_16x16x32_bf16 v[64:67], v[132:135], v[184:187], 0
	v_mfma_f32_16x16x32_bf16 v[72:75], v[160:163], v[184:187], 0
	v_mfma_f32_16x16x32_bf16 v[92:95], v[132:135], v[192:195], 0
	v_mfma_f32_16x16x32_bf16 v[96:99], v[160:163], v[192:195], 0
	v_mfma_f32_16x16x32_bf16 v[116:119], v[132:135], v[214:217], 0
	v_mfma_f32_16x16x32_bf16 v[124:127], v[160:163], v[214:217], 0
	v_mfma_f32_16x16x32_bf16 v[112:115], v[132:135], v[222:225], 0
	v_mfma_f32_16x16x32_bf16 v[100:103], v[160:163], v[222:225], 0
	v_mfma_f32_16x16x32_bf16 v[64:67], v[140:143], v[188:191], v[64:67]
	v_mfma_f32_16x16x32_bf16 v[72:75], v[164:167], v[188:191], v[72:75]
	v_mfma_f32_16x16x32_bf16 v[92:95], v[140:143], v[196:199], v[92:95]
	v_mfma_f32_16x16x32_bf16 v[96:99], v[164:167], v[196:199], v[96:99]
	v_mfma_f32_16x16x32_bf16 v[116:119], v[140:143], v[218:221], v[116:119]
	v_mfma_f32_16x16x32_bf16 v[124:127], v[164:167], v[218:221], v[124:127]
	v_mfma_f32_16x16x32_bf16 v[112:115], v[140:143], v[226:229], v[112:115]
	v_mfma_f32_16x16x32_bf16 v[100:103], v[164:167], v[226:229], v[100:103]
	s_setprio 0
	s_setprio 1
	v_mfma_f32_16x16x32_bf16 v[76:79], v[168:171], v[184:187], 0
	v_mfma_f32_16x16x32_bf16 v[84:87], v[176:179], v[184:187], 0
	v_mfma_f32_16x16x32_bf16 v[104:107], v[168:171], v[192:195], 0
	v_mfma_f32_16x16x32_bf16 v[108:111], v[176:179], v[192:195], 0
	v_mfma_f32_16x16x32_bf16 v[128:131], v[168:171], v[214:217], 0
	v_mfma_f32_16x16x32_bf16 v[120:123], v[176:179], v[214:217], 0
	v_mfma_f32_16x16x32_bf16 v[88:91], v[168:171], v[222:225], 0
	v_mfma_f32_16x16x32_bf16 v[80:83], v[176:179], v[222:225], 0
	v_mfma_f32_16x16x32_bf16 v[76:79], v[172:175], v[188:191], v[76:79]
	v_mfma_f32_16x16x32_bf16 v[84:87], v[180:183], v[188:191], v[84:87]
	v_mfma_f32_16x16x32_bf16 v[104:107], v[172:175], v[196:199], v[104:107]
	v_mfma_f32_16x16x32_bf16 v[108:111], v[180:183], v[196:199], v[108:111]
	v_mfma_f32_16x16x32_bf16 v[128:131], v[172:175], v[218:221], v[128:131]
	v_mfma_f32_16x16x32_bf16 v[120:123], v[180:183], v[218:221], v[120:123]
	v_mfma_f32_16x16x32_bf16 v[88:91], v[172:175], v[226:229], v[88:91]
	v_mfma_f32_16x16x32_bf16 v[80:83], v[180:183], v[226:229], v[80:83]
	s_setprio 0
	s_barrier
	s_add_i32 s86, s87, s40
	v_lshl_add_u64 v[200:201], s[72:73], 0, v[146:147]
	s_mov_b32 m0, s86
	ds_read_b128 v[184:187], v159 offset:16384
	ds_read_b128 v[188:191], v159 offset:17408
	ds_read_b128 v[192:195], v159 offset:18432
	ds_read_b128 v[196:199], v159 offset:19456
	ds_read_b128 v[214:217], v159 offset:20480
	ds_read_b128 v[218:221], v159 offset:21504
	ds_read_b128 v[222:225], v159 offset:22528
	ds_read_b128 v[226:229], v159 offset:23552
	global_load_lds_dwordx4 v[200:201], off
	s_add_i32 m0, s86, 0x2000
	s_add_u32 s86, s72, 0x40000
	v_lshl_add_u64 v[230:231], s[72:73], 0, v[148:149]
	s_addc_u32 s87, s73, 0
	s_add_i32 s83, s83, s40
	global_load_lds_dwordx4 v[230:231], off
	v_lshl_add_u64 v[232:233], s[86:87], 0, v[146:147]
	s_mov_b32 m0, s83
	v_lshl_add_u64 v[234:235], s[74:75], 0, v[148:149]
	global_load_lds_dwordx4 v[232:233], off
	v_lshl_add_u64 v[232:233], s[86:87], 0, v[148:149]
	s_add_i32 m0, s83, 0x2000
	s_nop 0
	global_load_lds_dwordx4 v[232:233], off
	v_lshl_add_u64 v[232:233], s[74:75], 0, v[146:147]
	s_mov_b32 m0, s19
	s_nop 0
	global_load_lds_dwordx4 v[232:233], off
	s_mov_b32 m0, s76
	s_nop 0
	global_load_lds_dwordx4 v[234:235], off
	s_waitcnt vmcnt(8)
	s_waitcnt lgkmcnt(0)
	s_barrier
; #define PG8_STAGE(bufoff, gbase, voff) do { _Pragma("unroll") for (int _i = 0; _i < 2; ++_i) \
;         __builtin_amdgcn_global_load_lds((const unsigned*)((const char*)(gbase) + (voff)[_i]), (LAS unsigned*)(lds + (bufoff) + ldsw + _i * 8192), 16, 0, 0); } while (0)
; #define PG8_LDA(dst, b, h) do { _Pragma("unroll") for (int m = 0; m < 4; ++m) _Pragma("unroll") for (int k = 0; k < 2; ++k) dst[m][k] = *(const LAS bf16x8*)(lds + PG8_SA(b, h) + aoff + m * 2048 + k * 1024); } while (0)
; #define PG8_LDB(dst, b, h) do { _Pragma("unroll") for (int n = 0; n < 2; ++n) _Pragma("unroll") for (int k = 0; k < 2; ++k) dst[n][k] = *(const LAS bf16x8*)(lds + PG8_SB(b, h) + boff + n * 2048 + k * 1024); } while (0)
; #define PG8_MMA(ai, bj, At, Bt) do { __builtin_amdgcn_s_setprio(1); _Pragma("unroll") for (int m = 0; m < 4; ++m) _Pragma("unroll") for (int n = 0; n < 2; ++n) _Pragma("unroll") for (int k = 0; k < 2; ++k) \
;         acc[ai][bj][m][n] = __builtin_amdgcn_mfma_f32_16x16x32_bf16(Bt[n][k], At[m][k], acc[ai][bj][m][n], 0, 0, 0); __builtin_amdgcn_s_setprio(0); } while (0)
; #define PG8_WAIT_V(n) asm volatile("s_waitcnt vmcnt(" #n ")" ::: "memory")
; #define PG8_WAIT_L(n) asm volatile("s_waitcnt lgkmcnt(" #n ")" ::: "memory")
; #define PG8_BAR __builtin_amdgcn_s_barrier()
; #define PG8_SCHED __builtin_amdgcn_sched_barrier(0)
; template <class Epi>
; __device__ __forceinline__ void gemm_phase(LAS unsigned char* lds, const Gemm g, const int G, const int cidx, const Epi& E) {
;     ...
;             PG8_WAIT_V(8); PG8_WAIT_L(0); PG8_BAR; PG8_MMA(1, 0, At, B0); PG8_MMA(1, 1, At, B1); PG8_BAR; PG8_SCHED;
;             PG8_LDB(B0, 1, 0); PG8_LDB(B1, 1, 1); PG8_SCHED; PG8_LDA(At, 1, 0); PG8_STAGE(PG8_SA(0, 1), a2 + hstep, voffA);
;             PG8_WAIT_V(8); PG8_WAIT_L(0); PG8_BAR; PG8_MMA(0, 0, At, B0); PG8_MMA(0, 1, At, B1); PG8_BAR; PG8_SCHED;
	s_setprio 1
	s_waitcnt lgkmcnt(0)
	v_mfma_f32_16x16x32_bf16 v[68:71], v[132:135], v[184:187], 0
	v_mfma_f32_16x16x32_bf16 v[60:63], v[160:163], v[184:187], 0
	v_mfma_f32_16x16x32_bf16 v[48:51], v[132:135], v[192:195], 0
	v_mfma_f32_16x16x32_bf16 v[44:47], v[160:163], v[192:195], 0
	v_mfma_f32_16x16x32_bf16 v[32:35], v[132:135], v[214:217], 0
	v_mfma_f32_16x16x32_bf16 v[28:31], v[160:163], v[214:217], 0
	v_mfma_f32_16x16x32_bf16 v[16:19], v[132:135], v[222:225], 0
	v_mfma_f32_16x16x32_bf16 v[12:15], v[160:163], v[222:225], 0
	v_mfma_f32_16x16x32_bf16 v[68:71], v[140:143], v[188:191], v[68:71]
	v_mfma_f32_16x16x32_bf16 v[60:63], v[164:167], v[188:191], v[60:63]
	v_mfma_f32_16x16x32_bf16 v[48:51], v[140:143], v[196:199], v[48:51]
	v_mfma_f32_16x16x32_bf16 v[44:47], v[164:167], v[196:199], v[44:47]
	v_mfma_f32_16x16x32_bf16 v[32:35], v[140:143], v[218:221], v[32:35]
	v_mfma_f32_16x16x32_bf16 v[28:31], v[164:167], v[218:221], v[28:31]
	v_mfma_f32_16x16x32_bf16 v[16:19], v[140:143], v[226:229], v[16:19]
	v_mfma_f32_16x16x32_bf16 v[12:15], v[164:167], v[226:229], v[12:15]
	s_setprio 0
	s_setprio 1
	v_mfma_f32_16x16x32_bf16 v[56:59], v[168:171], v[184:187], 0
	v_mfma_f32_16x16x32_bf16 v[52:55], v[176:179], v[184:187], 0
	v_mfma_f32_16x16x32_bf16 v[40:43], v[168:171], v[192:195], 0
	v_mfma_f32_16x16x32_bf16 v[36:39], v[176:179], v[192:195], 0
	v_mfma_f32_16x16x32_bf16 v[24:27], v[168:171], v[214:217], 0
	v_mfma_f32_16x16x32_bf16 v[20:23], v[176:179], v[214:217], 0
	v_mfma_f32_16x16x32_bf16 v[8:11], v[168:171], v[222:225], 0
	v_mfma_f32_16x16x32_bf16 v[4:7], v[176:179], v[222:225], 0
	v_mfma_f32_16x16x32_bf16 v[56:59], v[172:175], v[188:191], v[56:59]
	v_mfma_f32_16x16x32_bf16 v[52:55], v[180:183], v[188:191], v[52:55]
	v_mfma_f32_16x16x32_bf16 v[40:43], v[172:175], v[196:199], v[40:43]
	v_mfma_f32_16x16x32_bf16 v[36:39], v[180:183], v[196:199], v[36:39]
	v_mfma_f32_16x16x32_bf16 v[24:27], v[172:175], v[218:221], v[24:27]
	v_mfma_f32_16x16x32_bf16 v[20:23], v[180:183], v[218:221], v[20:23]
	v_mfma_f32_16x16x32_bf16 v[8:11], v[172:175], v[226:229], v[8:11]
	v_mfma_f32_16x16x32_bf16 v[4:7], v[180:183], v[226:229], v[4:7]
	s_setprio 0
	s_barrier
	s_add_i32 s83, 0, 0x18000
	v_add_u32_e32 v3, s83, v158
	s_add_i32 s86, 0, 0x1c000
	ds_read_b128 v[132:135], v3
	ds_read_b128 v[140:143], v3 offset:1024
	ds_read_b128 v[160:163], v3 offset:2048
	ds_read_b128 v[164:167], v3 offset:3072
	v_add_u32_e32 v3, s86, v158
	ds_read_b128 v[168:171], v3
	ds_read_b128 v[172:175], v3 offset:1024
	ds_read_b128 v[176:179], v3 offset:2048
	ds_read_b128 v[180:183], v3 offset:3072
	s_add_u32 s74, s74, 0x40000
	s_addc_u32 s75, s75, 0
	s_mov_b32 m0, s84
	v_lshl_add_u64 v[236:237], s[74:75], 0, v[146:147]
	ds_read_b128 v[184:187], v159 offset:32768
	ds_read_b128 v[188:191], v159 offset:33792
	ds_read_b128 v[192:195], v159 offset:34816
	ds_read_b128 v[196:199], v159 offset:35840
	ds_read_b128 v[214:217], v159 offset:36864
	ds_read_b128 v[218:221], v159 offset:37888
	ds_read_b128 v[222:225], v159 offset:38912
	ds_read_b128 v[226:229], v159 offset:39936
	global_load_lds_dwordx4 v[236:237], off
	v_lshl_add_u64 v[236:237], s[74:75], 0, v[148:149]
	s_mov_b32 m0, s97
	s_nop 0
	global_load_lds_dwordx4 v[236:237], off
	s_waitcnt vmcnt(8)
	s_waitcnt lgkmcnt(0)
	s_barrier
	s_setprio 1
	s_waitcnt lgkmcnt(0)
	v_mfma_f32_16x16x32_bf16 v[64:67], v[132:135], v[184:187], v[64:67]
	v_mfma_f32_16x16x32_bf16 v[72:75], v[160:163], v[184:187], v[72:75]
	v_mfma_f32_16x16x32_bf16 v[92:95], v[132:135], v[192:195], v[92:95]
	v_mfma_f32_16x16x32_bf16 v[96:99], v[160:163], v[192:195], v[96:99]
	v_mfma_f32_16x16x32_bf16 v[116:119], v[132:135], v[214:217], v[116:119]
	v_mfma_f32_16x16x32_bf16 v[124:127], v[160:163], v[214:217], v[124:127]
	v_mfma_f32_16x16x32_bf16 v[112:115], v[132:135], v[222:225], v[112:115]
	v_mfma_f32_16x16x32_bf16 v[100:103], v[160:163], v[222:225], v[100:103]
	v_mfma_f32_16x16x32_bf16 v[64:67], v[140:143], v[188:191], v[64:67]
	v_mfma_f32_16x16x32_bf16 v[72:75], v[164:167], v[188:191], v[72:75]
	v_mfma_f32_16x16x32_bf16 v[92:95], v[140:143], v[196:199], v[92:95]
	v_mfma_f32_16x16x32_bf16 v[96:99], v[164:167], v[196:199], v[96:99]
	v_mfma_f32_16x16x32_bf16 v[116:119], v[140:143], v[218:221], v[116:119]
	v_mfma_f32_16x16x32_bf16 v[124:127], v[164:167], v[218:221], v[124:127]
	v_mfma_f32_16x16x32_bf16 v[112:115], v[140:143], v[226:229], v[112:115]
	v_mfma_f32_16x16x32_bf16 v[100:103], v[164:167], v[226:229], v[100:103]
	s_setprio 0
	s_setprio 1
	v_mfma_f32_16x16x32_bf16 v[76:79], v[168:171], v[184:187], v[76:79]
	v_mfma_f32_16x16x32_bf16 v[84:87], v[176:179], v[184:187], v[84:87]
	v_mfma_f32_16x16x32_bf16 v[104:107], v[168:171], v[192:195], v[104:107]
	v_mfma_f32_16x16x32_bf16 v[108:111], v[176:179], v[192:195], v[108:111]
	v_mfma_f32_16x16x32_bf16 v[128:131], v[168:171], v[214:217], v[128:131]
	v_mfma_f32_16x16x32_bf16 v[120:123], v[176:179], v[214:217], v[120:123]
	v_mfma_f32_16x16x32_bf16 v[88:91], v[168:171], v[222:225], v[88:91]
	v_mfma_f32_16x16x32_bf16 v[80:83], v[176:179], v[222:225], v[80:83]
	v_mfma_f32_16x16x32_bf16 v[76:79], v[172:175], v[188:191], v[76:79]
	v_mfma_f32_16x16x32_bf16 v[84:87], v[180:183], v[188:191], v[84:87]
	v_mfma_f32_16x16x32_bf16 v[104:107], v[172:175], v[196:199], v[104:107]
	v_mfma_f32_16x16x32_bf16 v[108:111], v[180:183], v[196:199], v[108:111]
	v_mfma_f32_16x16x32_bf16 v[128:131], v[172:175], v[218:221], v[128:131]
	v_mfma_f32_16x16x32_bf16 v[120:123], v[180:183], v[218:221], v[120:123]
	v_mfma_f32_16x16x32_bf16 v[88:91], v[172:175], v[226:229], v[88:91]
	v_mfma_f32_16x16x32_bf16 v[80:83], v[180:183], v[226:229], v[80:83]
	s_setprio 0
	s_barrier
; #define PG8_STAGE(bufoff, gbase, voff) do { _Pragma("unroll") for (int _i = 0; _i < 2; ++_i) \
;         __builtin_amdgcn_global_load_lds((const unsigned*)((const char*)(gbase) + (voff)[_i]), (LAS unsigned*)(lds + (bufoff) + ldsw + _i * 8192), 16, 0, 0); } while (0)
; #define PG8_LDA(dst, b, h) do { _Pragma("unroll") for (int m = 0; m < 4; ++m) _Pragma("unroll") for (int k = 0; k < 2; ++k) dst[m][k] = *(const LAS bf16x8*)(lds + PG8_SA(b, h) + aoff + m * 2048 + k * 1024); } while (0)
; #define PG8_MMA(ai, bj, At, Bt) do { __builtin_amdgcn_s_setprio(1); _Pragma("unroll") for (int m = 0; m < 4; ++m) _Pragma("unroll") for (int n = 0; n < 2; ++n) _Pragma("unroll") for (int k = 0; k < 2; ++k) \
;         acc[ai][bj][m][n] = __builtin_amdgcn_mfma_f32_16x16x32_bf16(Bt[n][k], At[m][k], acc[ai][bj][m][n], 0, 0, 0); __builtin_amdgcn_s_setprio(0); } while (0)
; #define PG8_WAIT_V(n) asm volatile("s_waitcnt vmcnt(" #n ")" ::: "memory")
; #define PG8_WAIT_L(n) asm volatile("s_waitcnt lgkmcnt(" #n ")" ::: "memory")
; #define PG8_BAR __builtin_amdgcn_s_barrier()
; #define PG8_SCHED __builtin_amdgcn_sched_barrier(0)
; template <class Epi>
; __device__ __forceinline__ void gemm_phase(LAS unsigned char* lds, const Gemm g, const int G, const int cidx, const Epi& E) {
;     ...
;             PG8_LDA(At, 1, 1); PG8_STAGE(PG8_SB(1, 0), b3, voffB); PG8_STAGE(PG8_SB(1, 1), b3 + hstep, voffB); PG8_STAGE(PG8_SA(1, 0), a3, voffA);
;             PG8_WAIT_V(8); PG8_WAIT_L(0); PG8_BAR; PG8_MMA(1, 0, At, B0); PG8_MMA(1, 1, At, B1); PG8_BAR; PG8_SCHED;
;         }
	s_add_i32 s74, s83, s40
	v_lshl_add_u64 v[200:201], v[200:201], 0, s[46:47]
	s_mov_b32 m0, s74
	ds_read_b128 v[184:187], v159 offset:49152
	ds_read_b128 v[188:191], v159 offset:50176
	ds_read_b128 v[192:195], v159 offset:51200
	ds_read_b128 v[196:199], v159 offset:52224
	ds_read_b128 v[214:217], v159 offset:53248
	ds_read_b128 v[218:221], v159 offset:54272
	ds_read_b128 v[222:225], v159 offset:55296
	ds_read_b128 v[226:229], v159 offset:56320
	global_load_lds_dwordx4 v[200:201], off
	s_add_i32 m0, s74, 0x2000
	s_add_u32 s72, s72, 0x40080
	v_lshl_add_u64 v[200:201], v[230:231], 0, s[46:47]
	s_addc_u32 s73, s73, 0
	s_add_i32 s74, s86, s40
	global_load_lds_dwordx4 v[200:201], off
	v_lshl_add_u64 v[200:201], s[72:73], 0, v[146:147]
	s_mov_b32 m0, s74
	s_nop 0
	global_load_lds_dwordx4 v[200:201], off
	v_lshl_add_u64 v[200:201], s[72:73], 0, v[148:149]
	s_add_i32 m0, s74, 0x2000
	s_nop 0
	global_load_lds_dwordx4 v[200:201], off
	v_lshl_add_u64 v[200:201], v[232:233], 0, s[46:47]
	s_mov_b32 m0, s0
	s_nop 0
	global_load_lds_dwordx4 v[200:201], off
	v_lshl_add_u64 v[200:201], v[234:235], 0, s[46:47]
	s_mov_b32 m0, s2
	s_nop 0
	global_load_lds_dwordx4 v[200:201], off
	s_waitcnt vmcnt(8)
	s_waitcnt lgkmcnt(0)
	s_barrier
	s_setprio 1
	s_waitcnt lgkmcnt(0)
	v_mfma_f32_16x16x32_bf16 v[68:71], v[132:135], v[184:187], v[68:71]
	v_mfma_f32_16x16x32_bf16 v[60:63], v[160:163], v[184:187], v[60:63]
	v_mfma_f32_16x16x32_bf16 v[48:51], v[132:135], v[192:195], v[48:51]
	v_mfma_f32_16x16x32_bf16 v[44:47], v[160:163], v[192:195], v[44:47]
	v_mfma_f32_16x16x32_bf16 v[32:35], v[132:135], v[214:217], v[32:35]
	v_mfma_f32_16x16x32_bf16 v[28:31], v[160:163], v[214:217], v[28:31]
	v_mfma_f32_16x16x32_bf16 v[16:19], v[132:135], v[222:225], v[16:19]
	v_mfma_f32_16x16x32_bf16 v[12:15], v[160:163], v[222:225], v[12:15]
	v_mfma_f32_16x16x32_bf16 v[68:71], v[140:143], v[188:191], v[68:71]
	v_mfma_f32_16x16x32_bf16 v[60:63], v[164:167], v[188:191], v[60:63]
	v_mfma_f32_16x16x32_bf16 v[48:51], v[140:143], v[196:199], v[48:51]
	v_mfma_f32_16x16x32_bf16 v[44:47], v[164:167], v[196:199], v[44:47]
	v_mfma_f32_16x16x32_bf16 v[32:35], v[140:143], v[218:221], v[32:35]
	v_mfma_f32_16x16x32_bf16 v[28:31], v[164:167], v[218:221], v[28:31]
	v_mfma_f32_16x16x32_bf16 v[16:19], v[140:143], v[226:229], v[16:19]
	v_mfma_f32_16x16x32_bf16 v[12:15], v[164:167], v[226:229], v[12:15]
	s_setprio 0
	s_setprio 1
	v_mfma_f32_16x16x32_bf16 v[56:59], v[168:171], v[184:187], v[56:59]
	v_mfma_f32_16x16x32_bf16 v[52:55], v[176:179], v[184:187], v[52:55]
	v_mfma_f32_16x16x32_bf16 v[40:43], v[168:171], v[192:195], v[40:43]
	v_mfma_f32_16x16x32_bf16 v[36:39], v[176:179], v[192:195], v[36:39]
	v_mfma_f32_16x16x32_bf16 v[24:27], v[168:171], v[214:217], v[24:27]
	v_mfma_f32_16x16x32_bf16 v[20:23], v[176:179], v[214:217], v[20:23]
	v_mfma_f32_16x16x32_bf16 v[8:11], v[168:171], v[222:225], v[8:11]
	v_mfma_f32_16x16x32_bf16 v[4:7], v[176:179], v[222:225], v[4:7]
	v_mfma_f32_16x16x32_bf16 v[56:59], v[172:175], v[188:191], v[56:59]
	v_mfma_f32_16x16x32_bf16 v[52:55], v[180:183], v[188:191], v[52:55]
	v_mfma_f32_16x16x32_bf16 v[40:43], v[172:175], v[196:199], v[40:43]
	v_mfma_f32_16x16x32_bf16 v[36:39], v[180:183], v[196:199], v[36:39]
	v_mfma_f32_16x16x32_bf16 v[24:27], v[172:175], v[218:221], v[24:27]
	v_mfma_f32_16x16x32_bf16 v[20:23], v[180:183], v[218:221], v[20:23]
	v_mfma_f32_16x16x32_bf16 v[8:11], v[172:175], v[226:229], v[8:11]
	v_mfma_f32_16x16x32_bf16 v[4:7], v[180:183], v[226:229], v[4:7]
	s_setprio 0
	s_barrier
	s_add_i32 s77, s77, 2
	s_add_u32 s70, s70, 0x100
	s_addc_u32 s71, s71, 0
	.p2alignl 6, 3212836864

; __device__ __forceinline__ int opaque_bid() { int t = blockIdx.x; asm volatile("" : "+s"(t)); return t; }
; __device__ __forceinline__ int opaque_gd() { int t = gridDim.x; asm volatile("" : "+s"(t)); return t; }
; #define BG_STAGE(kk_, slot_) do { const int _n = (kk_) >> 2, _kt = (kk_) & 3; const int _so = (slot_) * STG; \
;         const bf16_t* _a = outs + ((size_t)_n * M + (size_t)pm * 256) * 256 + _kt * 64; const bf16_t* _b = wbr + ((size_t)_n * 1024 + (size_t)pn * 128) * 256 + _kt * 64; \
;         BG_LD(_so, _a); BG_LD(_so + HTB, _a + 128 * 256); BG_LDX(_so + 2 * HTB, _b, voffB); } while (0)
; __device__ __forceinline__ void bgemm_phase(LAS unsigned char* lds, const bf16_t* outs, const bf16_t* wbr, const bf16_t* zg, bf16_t* merged) {
;     ...
;     for (int u = opaque_bid(); u < 512; u += opaque_gd()) {
;         const int up = (u & ~255) + (u & 7) * 32 + ((u & 255) >> 3);
;         const int pm = up >> 3, pn = up & 7;
;         f32x4 tot[4][4], acc[4][4];
; #pragma unroll
;         for (int mi = 0; mi < 4; ++mi)
; #pragma unroll
;             for (int ni = 0; ni < 4; ++ni) { tot[mi][ni] = ZERO4; acc[mi][ni] = ZERO4; }
;         BG_STAGE(0, 0); BG_STAGE(1, 1);
;         int slot = 0;
.LBB0_295:
	s_lshl_b32 s13, s0, 5
	s_and_b32 s12, s0, 0xffffff00
	s_and_b32 s13, s13, 0xe0
	s_or_b32 s12, s13, s12
	s_lshr_b32 s13, s0, 3
	s_and_b32 s13, s13, 24
	s_or_b32 s35, s12, s13
	s_ashr_i32 s12, s35, 3
	s_ashr_i32 s13, s12, 31
	s_bfe_u32 s36, s0, 0x30003
	s_lshl_b64 s[16:17], s[12:13], 17
	s_add_u32 s14, s6, s16
	s_addc_u32 s15, s7, s17
	s_lshl_b32 s20, s36, 16
	s_add_i32 s42, s30, 0x2000
	s_mov_b32 m0, s30
	v_lshl_add_u64 v[4:5], s[14:15], 0, v[104:105]
	s_add_u32 s18, s14, 0x10000
	global_load_lds_dwordx4 v[4:5], off
	v_lshl_add_u64 v[6:7], s[14:15], 0, v[100:101]
	s_mov_b32 m0, s42
	s_addc_u32 s19, s15, 0
	s_add_i32 s41, s30, 0x4000
	global_load_lds_dwordx4 v[6:7], off
	v_lshl_add_u64 v[8:9], s[18:19], 0, v[104:105]
	s_mov_b32 m0, s41
	s_add_i32 s40, s30, 0x6000
	global_load_lds_dwordx4 v[8:9], off
	v_lshl_add_u64 v[8:9], s[18:19], 0, v[100:101]
	s_add_u32 s18, s2, s20
	s_mov_b32 m0, s40
	s_addc_u32 s19, s23, 0
	s_add_i32 s39, s30, 0x8000
	global_load_lds_dwordx4 v[8:9], off
	v_lshl_add_u64 v[8:9], s[18:19], 0, v[102:103]
	s_mov_b32 m0, s39
	s_add_i32 s38, s30, 0xa000
	global_load_lds_dwordx4 v[8:9], off
	v_lshl_add_u64 v[10:11], s[18:19], 0, v[0:1]
	s_mov_b32 m0, s38
	v_lshl_add_u64 v[4:5], v[4:5], 0, s[46:47]
	global_load_lds_dwordx4 v[10:11], off
	s_add_i32 m0, s30, 0xc000
	v_mov_b32_e32 v116, 0
	global_load_lds_dwordx4 v[4:5], off
	s_add_i32 m0, s30, 0xe000
	s_add_u32 s20, s14, 0x10080
	v_lshl_add_u64 v[4:5], v[6:7], 0, s[46:47]
	s_addc_u32 s21, s15, 0
	global_load_lds_dwordx4 v[4:5], off
	v_lshl_add_u64 v[4:5], s[20:21], 0, v[104:105]
	s_add_i32 m0, s30, 0x10000
	s_lshl_b32 s37, s36, 15
	global_load_lds_dwordx4 v[4:5], off
	v_lshl_add_u64 v[4:5], s[20:21], 0, v[100:101]
	s_add_i32 m0, s30, 0x12000
	s_lshl_b64 s[12:13], s[12:13], 18
	global_load_lds_dwordx4 v[4:5], off
	v_lshl_add_u64 v[4:5], v[8:9], 0, s[46:47]
	s_add_i32 m0, s30, 0x14000
	s_or_b32 s20, s12, s37
	global_load_lds_dwordx4 v[4:5], off
	v_lshl_add_u64 v[4:5], v[10:11], 0, s[46:47]
	s_add_i32 m0, s30, 0x16000
	s_mov_b32 s21, s13
	global_load_lds_dwordx4 v[4:5], off
	v_lshl_add_u64 v[194:195], s[20:21], 0, v[106:107]
	v_lshl_add_u64 v[196:197], v[112:113], 0, s[16:17]
	v_lshl_add_u64 v[198:199], v[114:115], 0, s[16:17]
	s_mov_b32 s16, 0
	s_mov_b64 s[20:21], 0
	s_mov_b64 s[26:27], s[18:19]
	v_mov_b32_e32 v117, v116
	v_mov_b32_e32 v118, v116
	v_mov_b32_e32 v119, v116
	v_mov_b32_e32 v120, v116
	v_mov_b32_e32 v121, v116
	v_mov_b32_e32 v122, v116
	v_mov_b32_e32 v123, v116
	v_mov_b32_e32 v124, v116
	v_mov_b32_e32 v125, v116
	v_mov_b32_e32 v126, v116
	v_mov_b32_e32 v127, v116
	v_mov_b32_e32 v128, v116
	v_mov_b32_e32 v129, v116
	v_mov_b32_e32 v130, v116
	v_mov_b32_e32 v131, v116
	v_mov_b32_e32 v146, v116
	v_mov_b32_e32 v147, v116
	v_mov_b32_e32 v148, v116
	v_mov_b32_e32 v149, v116
	v_mov_b32_e32 v150, v116
	v_mov_b32_e32 v151, v116
	v_mov_b32_e32 v152, v116
	v_mov_b32_e32 v153, v116
	v_mov_b32_e32 v154, v116
	v_mov_b32_e32 v155, v116
	v_mov_b32_e32 v156, v116
	v_mov_b32_e32 v157, v116
	v_mov_b32_e32 v158, v116
	v_mov_b32_e32 v159, v116
	v_mov_b32_e32 v160, v116
	v_mov_b32_e32 v161, v116
	v_mov_b32_e32 v162, v116
	v_mov_b32_e32 v163, v116
	v_mov_b32_e32 v164, v116
	v_mov_b32_e32 v165, v116
	v_mov_b32_e32 v166, v116
	v_mov_b32_e32 v167, v116
	v_mov_b32_e32 v168, v116
	v_mov_b32_e32 v169, v116
	v_mov_b32_e32 v170, v116
	v_mov_b32_e32 v171, v116
	v_mov_b32_e32 v172, v116
	v_mov_b32_e32 v173, v116
	v_mov_b32_e32 v174, v116
	v_mov_b32_e32 v175, v116
	v_mov_b32_e32 v176, v116
	v_mov_b32_e32 v177, v116
	v_mov_b32_e32 v178, v116
	v_mov_b32_e32 v179, v116
	v_mov_b32_e32 v180, v116
	v_mov_b32_e32 v181, v116
	v_mov_b32_e32 v182, v116
	v_mov_b32_e32 v183, v116
	v_mov_b32_e32 v184, v116
	v_mov_b32_e32 v185, v116
	v_mov_b32_e32 v186, v116
	v_mov_b32_e32 v187, v116
	v_mov_b32_e32 v188, v116
	v_mov_b32_e32 v189, v116
	v_mov_b32_e32 v190, v116
	v_mov_b32_e32 v191, v116
	v_mov_b32_e32 v192, v116
	v_mov_b32_e32 v193, v116
	.p2alignl 6, 3212836864

; #define PG8_STAGE(bufoff, gbase, voff) do { _Pragma("unroll") for (int _i = 0; _i < 2; ++_i) \
;         __builtin_amdgcn_global_load_lds((const unsigned*)((const char*)(gbase) + (voff)[_i]), (LAS unsigned*)(lds + (bufoff) + ldsw + _i * 8192), 16, 0, 0); } while (0)
; #define PG8_LDA(dst, b, h) do { _Pragma("unroll") for (int m = 0; m < 4; ++m) _Pragma("unroll") for (int k = 0; k < 2; ++k) dst[m][k] = *(const LAS bf16x8*)(lds + PG8_SA(b, h) + aoff + m * 2048 + k * 1024); } while (0)
; #define PG8_LDB(dst, b, h) do { _Pragma("unroll") for (int n = 0; n < 2; ++n) _Pragma("unroll") for (int k = 0; k < 2; ++k) dst[n][k] = *(const LAS bf16x8*)(lds + PG8_SB(b, h) + boff + n * 2048 + k * 1024); } while (0)
; #define PG8_MMA(ai, bj, At, Bt) do { __builtin_amdgcn_s_setprio(1); _Pragma("unroll") for (int m = 0; m < 4; ++m) _Pragma("unroll") for (int n = 0; n < 2; ++n) _Pragma("unroll") for (int k = 0; k < 2; ++k) \
;         acc[ai][bj][m][n] = __builtin_amdgcn_mfma_f32_16x16x32_bf16(Bt[n][k], At[m][k], acc[ai][bj][m][n], 0, 0, 0); __builtin_amdgcn_s_setprio(0); } while (0)
; #define PG8_WAIT_V(n) asm volatile("s_waitcnt vmcnt(" #n ")" ::: "memory")
; #define PG8_WAIT_L(n) asm volatile("s_waitcnt lgkmcnt(" #n ")" ::: "memory")
; template <class Epi>
; __device__ __forceinline__ void gemm_phase(LAS unsigned char* lds, const Gemm g, const int G, const int cidx, const Epi& E) {
;     ...
;         const char* nA = has_next ? PG8_ABASE(nxt) : cA; const char* nB = has_next ? (const char*)g.Bt + (size_t)nxt.pn * tstep : cB;
;         for (int t = 0; t < nt; t += 2) {
;             const bool last = (t == nt - 2);
;             const char* a1 = cA + (size_t)(t + 1) * kstep;
;             const char* a2 = last ? nA : cA + (size_t)(t + 2) * kstep; const char* b2 = last ? nB : cB + (size_t)(t + 2) * kstep;
;             const char* a3 = a2 + kstep; const char* b3 = b2 + kstep;
;             PG8_LDB(B0, 0, 0); PG8_LDB(B1, 0, 1); PG8_SCHED; PG8_LDA(At, 0, 0); PG8_STAGE(PG8_SA(1, 1), a1 + hstep, voffA);
;             PG8_WAIT_V(8); PG8_WAIT_L(0); PG8_BAR; PG8_MMA(0, 0, At, B0); PG8_MMA(0, 1, At, B1); PG8_BAR; PG8_SCHED;
;             PG8_LDA(At, 0, 1); PG8_STAGE(PG8_SB(0, 0), b2, voffB); PG8_STAGE(PG8_SB(0, 1), b2 + hstep, voffB); PG8_STAGE(PG8_SA(0, 0), a2, voffA);
;             PG8_WAIT_V(8); PG8_WAIT_L(0); PG8_BAR; PG8_MMA(1, 0, At, B0); PG8_MMA(1, 1, At, B1); PG8_BAR; PG8_SCHED;
.LBB0_449:
	s_add_u32 s43, s24, 0x100
	s_addc_u32 s44, s25, 0
	s_add_u32 s24, s10, 0xb0080
	s_addc_u32 s25, s11, 0
	v_lshl_add_u64 v[0:1], s[24:25], 0, v[150:151]
	v_lshl_add_u64 v[154:155], s[24:25], 0, v[152:153]
	s_mov_b32 s45, -2
	s_mov_b64 s[24:25], 0
	s_add_u32 s26, s10, s24
	s_addc_u32 s27, s11, s25
	s_add_u32 s26, s26, 0x100
	s_addc_u32 s27, s27, 0
	s_add_u32 s68, s43, s24
	s_addc_u32 s77, s44, s25
	s_add_i32 s83, 0, 0x10000
	s_cmpk_eq_i32 s24, 0x1500
	s_cselect_b32 s29, s21, s27
	s_cselect_b32 s28, s20, s26
	v_add_u32_e32 v3, s83, v157
	s_cselect_b32 s27, s9, s77
	s_cselect_b32 s26, s8, s68
	s_add_i32 s68, 0, 0x14000
	ds_read_b128 v[132:135], v3
	ds_read_b128 v[140:143], v3 offset:1024
	ds_read_b128 v[160:163], v3 offset:2048
	ds_read_b128 v[164:167], v3 offset:3072
	v_add_u32_e32 v3, s68, v157
	ds_read_b128 v[168:171], v3
	ds_read_b128 v[172:175], v3 offset:1024
	ds_read_b128 v[176:179], v3 offset:2048
	ds_read_b128 v[180:183], v3 offset:3072
	v_lshl_add_u64 v[200:201], v[154:155], 0, s[24:25]
	s_add_i32 m0, s71, 0xc000
	ds_read_b128 v[184:187], v159
	ds_read_b128 v[188:191], v159 offset:1024
	ds_read_b128 v[192:195], v159 offset:2048
	ds_read_b128 v[196:199], v159 offset:3072
	ds_read_b128 v[214:217], v159 offset:4096
	ds_read_b128 v[218:221], v159 offset:5120
	ds_read_b128 v[222:225], v159 offset:6144
	ds_read_b128 v[226:229], v159 offset:7168
	global_load_lds_dwordx4 v[200:201], off
	v_lshl_add_u64 v[200:201], v[0:1], 0, s[24:25]
	s_add_i32 m0, s71, 0xe000
	s_nop 0
	global_load_lds_dwordx4 v[200:201], off
	s_waitcnt vmcnt(8)
	s_waitcnt lgkmcnt(0)
	s_barrier
	s_setprio 1
	s_waitcnt lgkmcnt(0)
	v_mfma_f32_16x16x32_bf16 v[100:103], v[132:135], v[184:187], 0
	v_mfma_f32_16x16x32_bf16 v[108:111], v[160:163], v[184:187], 0
	v_mfma_f32_16x16x32_bf16 v[120:123], v[132:135], v[192:195], 0
	v_mfma_f32_16x16x32_bf16 v[128:131], v[160:163], v[192:195], 0
	v_mfma_f32_16x16x32_bf16 v[96:99], v[132:135], v[214:217], 0
	v_mfma_f32_16x16x32_bf16 v[92:95], v[160:163], v[214:217], 0
	v_mfma_f32_16x16x32_bf16 v[80:83], v[132:135], v[222:225], 0
	v_mfma_f32_16x16x32_bf16 v[76:79], v[160:163], v[222:225], 0
	v_mfma_f32_16x16x32_bf16 v[100:103], v[140:143], v[188:191], v[100:103]
	v_mfma_f32_16x16x32_bf16 v[108:111], v[164:167], v[188:191], v[108:111]
	v_mfma_f32_16x16x32_bf16 v[120:123], v[140:143], v[196:199], v[120:123]
	v_mfma_f32_16x16x32_bf16 v[128:131], v[164:167], v[196:199], v[128:131]
	v_mfma_f32_16x16x32_bf16 v[96:99], v[140:143], v[218:221], v[96:99]
	v_mfma_f32_16x16x32_bf16 v[92:95], v[164:167], v[218:221], v[92:95]
	v_mfma_f32_16x16x32_bf16 v[80:83], v[140:143], v[226:229], v[80:83]
	v_mfma_f32_16x16x32_bf16 v[76:79], v[164:167], v[226:229], v[76:79]
	s_setprio 0
	s_setprio 1
	v_mfma_f32_16x16x32_bf16 v[116:119], v[168:171], v[184:187], 0
	v_mfma_f32_16x16x32_bf16 v[124:127], v[176:179], v[184:187], 0
	v_mfma_f32_16x16x32_bf16 v[112:115], v[168:171], v[192:195], 0
	v_mfma_f32_16x16x32_bf16 v[104:107], v[176:179], v[192:195], 0
	v_mfma_f32_16x16x32_bf16 v[88:91], v[168:171], v[214:217], 0
	v_mfma_f32_16x16x32_bf16 v[84:87], v[176:179], v[214:217], 0
	v_mfma_f32_16x16x32_bf16 v[72:75], v[168:171], v[222:225], 0
	v_mfma_f32_16x16x32_bf16 v[68:71], v[176:179], v[222:225], 0
	v_mfma_f32_16x16x32_bf16 v[116:119], v[172:175], v[188:191], v[116:119]
	v_mfma_f32_16x16x32_bf16 v[124:127], v[180:183], v[188:191], v[124:127]
	v_mfma_f32_16x16x32_bf16 v[112:115], v[172:175], v[196:199], v[112:115]
	v_mfma_f32_16x16x32_bf16 v[104:107], v[180:183], v[196:199], v[104:107]
	v_mfma_f32_16x16x32_bf16 v[88:91], v[172:175], v[218:221], v[88:91]
	v_mfma_f32_16x16x32_bf16 v[84:87], v[180:183], v[218:221], v[84:87]
	v_mfma_f32_16x16x32_bf16 v[72:75], v[172:175], v[226:229], v[72:75]
	v_mfma_f32_16x16x32_bf16 v[68:71], v[180:183], v[226:229], v[68:71]
	s_setprio 0
	s_barrier
	s_add_i32 s77, s83, s70
	v_lshl_add_u64 v[200:201], s[26:27], 0, v[146:147]
	s_mov_b32 m0, s77
	ds_read_b128 v[184:187], v159 offset:16384
	ds_read_b128 v[188:191], v159 offset:17408
	ds_read_b128 v[192:195], v159 offset:18432
	ds_read_b128 v[196:199], v159 offset:19456
	ds_read_b128 v[214:217], v159 offset:20480
	ds_read_b128 v[218:221], v159 offset:21504
	ds_read_b128 v[222:225], v159 offset:22528
	ds_read_b128 v[226:229], v159 offset:23552
	global_load_lds_dwordx4 v[200:201], off
	s_add_i32 m0, s77, 0x2000
	s_add_u32 s86, s26, 0xb0000
	v_lshl_add_u64 v[230:231], s[26:27], 0, v[148:149]
	s_addc_u32 s87, s27, 0
	s_add_i32 s68, s68, s70
	global_load_lds_dwordx4 v[230:231], off
	v_lshl_add_u64 v[232:233], s[86:87], 0, v[146:147]
	s_mov_b32 m0, s68
	v_lshl_add_u64 v[234:235], s[28:29], 0, v[148:149]
	global_load_lds_dwordx4 v[232:233], off
	v_lshl_add_u64 v[232:233], s[86:87], 0, v[148:149]
	s_add_i32 m0, s68, 0x2000
	s_nop 0
	global_load_lds_dwordx4 v[232:233], off
	v_lshl_add_u64 v[232:233], s[28:29], 0, v[146:147]
	s_mov_b32 m0, s71
	s_nop 0
	global_load_lds_dwordx4 v[232:233], off
	s_mov_b32 m0, s72
	s_nop 0
	global_load_lds_dwordx4 v[234:235], off
	s_waitcnt vmcnt(8)
	s_waitcnt lgkmcnt(0)
	s_barrier
; #define PG8_STAGE(bufoff, gbase, voff) do { _Pragma("unroll") for (int _i = 0; _i < 2; ++_i) \
;         __builtin_amdgcn_global_load_lds((const unsigned*)((const char*)(gbase) + (voff)[_i]), (LAS unsigned*)(lds + (bufoff) + ldsw + _i * 8192), 16, 0, 0); } while (0)
; #define PG8_LDA(dst, b, h) do { _Pragma("unroll") for (int m = 0; m < 4; ++m) _Pragma("unroll") for (int k = 0; k < 2; ++k) dst[m][k] = *(const LAS bf16x8*)(lds + PG8_SA(b, h) + aoff + m * 2048 + k * 1024); } while (0)
; #define PG8_LDB(dst, b, h) do { _Pragma("unroll") for (int n = 0; n < 2; ++n) _Pragma("unroll") for (int k = 0; k < 2; ++k) dst[n][k] = *(const LAS bf16x8*)(lds + PG8_SB(b, h) + boff + n * 2048 + k * 1024); } while (0)
; #define PG8_MMA(ai, bj, At, Bt) do { __builtin_amdgcn_s_setprio(1); _Pragma("unroll") for (int m = 0; m < 4; ++m) _Pragma("unroll") for (int n = 0; n < 2; ++n) _Pragma("unroll") for (int k = 0; k < 2; ++k) \
;         acc[ai][bj][m][n] = __builtin_amdgcn_mfma_f32_16x16x32_bf16(Bt[n][k], At[m][k], acc[ai][bj][m][n], 0, 0, 0); __builtin_amdgcn_s_setprio(0); } while (0)
; #define PG8_WAIT_V(n) asm volatile("s_waitcnt vmcnt(" #n ")" ::: "memory")
; #define PG8_WAIT_L(n) asm volatile("s_waitcnt lgkmcnt(" #n ")" ::: "memory")
; #define PG8_BAR __builtin_amdgcn_s_barrier()
; #define PG8_SCHED __builtin_amdgcn_sched_barrier(0)
; template <class Epi>
; __device__ __forceinline__ void gemm_phase(LAS unsigned char* lds, const Gemm g, const int G, const int cidx, const Epi& E) {
;     ...
;             PG8_WAIT_V(8); PG8_WAIT_L(0); PG8_BAR; PG8_MMA(1, 0, At, B0); PG8_MMA(1, 1, At, B1); PG8_BAR; PG8_SCHED;
;             PG8_LDB(B0, 1, 0); PG8_LDB(B1, 1, 1); PG8_SCHED; PG8_LDA(At, 1, 0); PG8_STAGE(PG8_SA(0, 1), a2 + hstep, voffA);
;             PG8_WAIT_V(8); PG8_WAIT_L(0); PG8_BAR; PG8_MMA(0, 0, At, B0); PG8_MMA(0, 1, At, B1); PG8_BAR; PG8_SCHED;
	s_setprio 1
	s_waitcnt lgkmcnt(0)
	v_mfma_f32_16x16x32_bf16 v[64:67], v[132:135], v[184:187], 0
	v_mfma_f32_16x16x32_bf16 v[60:63], v[160:163], v[184:187], 0
	v_mfma_f32_16x16x32_bf16 v[48:51], v[132:135], v[192:195], 0
	v_mfma_f32_16x16x32_bf16 v[44:47], v[160:163], v[192:195], 0
	v_mfma_f32_16x16x32_bf16 v[32:35], v[132:135], v[214:217], 0
	v_mfma_f32_16x16x32_bf16 v[28:31], v[160:163], v[214:217], 0
	v_mfma_f32_16x16x32_bf16 v[16:19], v[132:135], v[222:225], 0
	v_mfma_f32_16x16x32_bf16 v[12:15], v[160:163], v[222:225], 0
	v_mfma_f32_16x16x32_bf16 v[64:67], v[140:143], v[188:191], v[64:67]
	v_mfma_f32_16x16x32_bf16 v[60:63], v[164:167], v[188:191], v[60:63]
	v_mfma_f32_16x16x32_bf16 v[48:51], v[140:143], v[196:199], v[48:51]
	v_mfma_f32_16x16x32_bf16 v[44:47], v[164:167], v[196:199], v[44:47]
	v_mfma_f32_16x16x32_bf16 v[32:35], v[140:143], v[218:221], v[32:35]
	v_mfma_f32_16x16x32_bf16 v[28:31], v[164:167], v[218:221], v[28:31]
	v_mfma_f32_16x16x32_bf16 v[16:19], v[140:143], v[226:229], v[16:19]
	v_mfma_f32_16x16x32_bf16 v[12:15], v[164:167], v[226:229], v[12:15]
	s_setprio 0
	s_setprio 1
	v_mfma_f32_16x16x32_bf16 v[56:59], v[168:171], v[184:187], 0
	v_mfma_f32_16x16x32_bf16 v[52:55], v[176:179], v[184:187], 0
	v_mfma_f32_16x16x32_bf16 v[40:43], v[168:171], v[192:195], 0
	v_mfma_f32_16x16x32_bf16 v[36:39], v[176:179], v[192:195], 0
	v_mfma_f32_16x16x32_bf16 v[24:27], v[168:171], v[214:217], 0
	v_mfma_f32_16x16x32_bf16 v[20:23], v[176:179], v[214:217], 0
	v_mfma_f32_16x16x32_bf16 v[8:11], v[168:171], v[222:225], 0
	v_mfma_f32_16x16x32_bf16 v[4:7], v[176:179], v[222:225], 0
	v_mfma_f32_16x16x32_bf16 v[56:59], v[172:175], v[188:191], v[56:59]
	v_mfma_f32_16x16x32_bf16 v[52:55], v[180:183], v[188:191], v[52:55]
	v_mfma_f32_16x16x32_bf16 v[40:43], v[172:175], v[196:199], v[40:43]
	v_mfma_f32_16x16x32_bf16 v[36:39], v[180:183], v[196:199], v[36:39]
	v_mfma_f32_16x16x32_bf16 v[24:27], v[172:175], v[218:221], v[24:27]
	v_mfma_f32_16x16x32_bf16 v[20:23], v[180:183], v[218:221], v[20:23]
	v_mfma_f32_16x16x32_bf16 v[8:11], v[172:175], v[226:229], v[8:11]
	v_mfma_f32_16x16x32_bf16 v[4:7], v[180:183], v[226:229], v[4:7]
	s_setprio 0
	s_barrier
	s_add_i32 s68, 0, 0x18000
	v_add_u32_e32 v3, s68, v157
	s_add_i32 s77, 0, 0x1c000
	ds_read_b128 v[132:135], v3
	ds_read_b128 v[140:143], v3 offset:1024
	ds_read_b128 v[160:163], v3 offset:2048
	ds_read_b128 v[164:167], v3 offset:3072
	v_add_u32_e32 v3, s77, v157
	ds_read_b128 v[168:171], v3
	ds_read_b128 v[172:175], v3 offset:1024
	ds_read_b128 v[176:179], v3 offset:2048
	ds_read_b128 v[180:183], v3 offset:3072
	s_add_u32 s28, s28, 0xb0000
	s_addc_u32 s29, s29, 0
	s_mov_b32 m0, s73
	v_lshl_add_u64 v[236:237], s[28:29], 0, v[146:147]
	ds_read_b128 v[184:187], v159 offset:32768
	ds_read_b128 v[188:191], v159 offset:33792
	ds_read_b128 v[192:195], v159 offset:34816
	ds_read_b128 v[196:199], v159 offset:35840
	ds_read_b128 v[214:217], v159 offset:36864
	ds_read_b128 v[218:221], v159 offset:37888
	ds_read_b128 v[222:225], v159 offset:38912
	ds_read_b128 v[226:229], v159 offset:39936
	global_load_lds_dwordx4 v[236:237], off
	v_lshl_add_u64 v[236:237], s[28:29], 0, v[148:149]
	s_mov_b32 m0, s74
	s_nop 0
	global_load_lds_dwordx4 v[236:237], off
	s_waitcnt vmcnt(8)
	s_waitcnt lgkmcnt(0)
	s_barrier
	s_setprio 1
	s_waitcnt lgkmcnt(0)
	v_mfma_f32_16x16x32_bf16 v[100:103], v[132:135], v[184:187], v[100:103]
	v_mfma_f32_16x16x32_bf16 v[108:111], v[160:163], v[184:187], v[108:111]
	v_mfma_f32_16x16x32_bf16 v[120:123], v[132:135], v[192:195], v[120:123]
	v_mfma_f32_16x16x32_bf16 v[128:131], v[160:163], v[192:195], v[128:131]
	v_mfma_f32_16x16x32_bf16 v[96:99], v[132:135], v[214:217], v[96:99]
	v_mfma_f32_16x16x32_bf16 v[92:95], v[160:163], v[214:217], v[92:95]
	v_mfma_f32_16x16x32_bf16 v[80:83], v[132:135], v[222:225], v[80:83]
	v_mfma_f32_16x16x32_bf16 v[76:79], v[160:163], v[222:225], v[76:79]
	v_mfma_f32_16x16x32_bf16 v[100:103], v[140:143], v[188:191], v[100:103]
	v_mfma_f32_16x16x32_bf16 v[108:111], v[164:167], v[188:191], v[108:111]
	v_mfma_f32_16x16x32_bf16 v[120:123], v[140:143], v[196:199], v[120:123]
	v_mfma_f32_16x16x32_bf16 v[128:131], v[164:167], v[196:199], v[128:131]
	v_mfma_f32_16x16x32_bf16 v[96:99], v[140:143], v[218:221], v[96:99]
	v_mfma_f32_16x16x32_bf16 v[92:95], v[164:167], v[218:221], v[92:95]
	v_mfma_f32_16x16x32_bf16 v[80:83], v[140:143], v[226:229], v[80:83]
	v_mfma_f32_16x16x32_bf16 v[76:79], v[164:167], v[226:229], v[76:79]
	s_setprio 0
	s_setprio 1
	v_mfma_f32_16x16x32_bf16 v[116:119], v[168:171], v[184:187], v[116:119]
	v_mfma_f32_16x16x32_bf16 v[124:127], v[176:179], v[184:187], v[124:127]
	v_mfma_f32_16x16x32_bf16 v[112:115], v[168:171], v[192:195], v[112:115]
	v_mfma_f32_16x16x32_bf16 v[104:107], v[176:179], v[192:195], v[104:107]
	v_mfma_f32_16x16x32_bf16 v[88:91], v[168:171], v[214:217], v[88:91]
	v_mfma_f32_16x16x32_bf16 v[84:87], v[176:179], v[214:217], v[84:87]
	v_mfma_f32_16x16x32_bf16 v[72:75], v[168:171], v[222:225], v[72:75]
	v_mfma_f32_16x16x32_bf16 v[68:71], v[176:179], v[222:225], v[68:71]
	v_mfma_f32_16x16x32_bf16 v[116:119], v[172:175], v[188:191], v[116:119]
	v_mfma_f32_16x16x32_bf16 v[124:127], v[180:183], v[188:191], v[124:127]
	v_mfma_f32_16x16x32_bf16 v[112:115], v[172:175], v[196:199], v[112:115]
	v_mfma_f32_16x16x32_bf16 v[104:107], v[180:183], v[196:199], v[104:107]
	v_mfma_f32_16x16x32_bf16 v[88:91], v[172:175], v[218:221], v[88:91]
	v_mfma_f32_16x16x32_bf16 v[84:87], v[180:183], v[218:221], v[84:87]
	v_mfma_f32_16x16x32_bf16 v[72:75], v[172:175], v[226:229], v[72:75]
	v_mfma_f32_16x16x32_bf16 v[68:71], v[180:183], v[226:229], v[68:71]
	s_setprio 0
	s_barrier
; #define PG8_STAGE(bufoff, gbase, voff) do { _Pragma("unroll") for (int _i = 0; _i < 2; ++_i) \
;         __builtin_amdgcn_global_load_lds((const unsigned*)((const char*)(gbase) + (voff)[_i]), (LAS unsigned*)(lds + (bufoff) + ldsw + _i * 8192), 16, 0, 0); } while (0)
; #define PG8_LDA(dst, b, h) do { _Pragma("unroll") for (int m = 0; m < 4; ++m) _Pragma("unroll") for (int k = 0; k < 2; ++k) dst[m][k] = *(const LAS bf16x8*)(lds + PG8_SA(b, h) + aoff + m * 2048 + k * 1024); } while (0)
; #define PG8_MMA(ai, bj, At, Bt) do { __builtin_amdgcn_s_setprio(1); _Pragma("unroll") for (int m = 0; m < 4; ++m) _Pragma("unroll") for (int n = 0; n < 2; ++n) _Pragma("unroll") for (int k = 0; k < 2; ++k) \
;         acc[ai][bj][m][n] = __builtin_amdgcn_mfma_f32_16x16x32_bf16(Bt[n][k], At[m][k], acc[ai][bj][m][n], 0, 0, 0); __builtin_amdgcn_s_setprio(0); } while (0)
; #define PG8_WAIT_V(n) asm volatile("s_waitcnt vmcnt(" #n ")" ::: "memory")
; #define PG8_WAIT_L(n) asm volatile("s_waitcnt lgkmcnt(" #n ")" ::: "memory")
; #define PG8_BAR __builtin_amdgcn_s_barrier()
; #define PG8_SCHED __builtin_amdgcn_sched_barrier(0)
; template <class Epi>
; __device__ __forceinline__ void gemm_phase(LAS unsigned char* lds, const Gemm g, const int G, const int cidx, const Epi& E) {
;     ...
;             PG8_LDA(At, 1, 1); PG8_STAGE(PG8_SB(1, 0), b3, voffB); PG8_STAGE(PG8_SB(1, 1), b3 + hstep, voffB); PG8_STAGE(PG8_SA(1, 0), a3, voffA);
;             PG8_WAIT_V(8); PG8_WAIT_L(0); PG8_BAR; PG8_MMA(1, 0, At, B0); PG8_MMA(1, 1, At, B1); PG8_BAR; PG8_SCHED;
;         }
	s_add_i32 s28, s68, s70
	v_lshl_add_u64 v[200:201], v[200:201], 0, s[46:47]
	s_mov_b32 m0, s28
	ds_read_b128 v[184:187], v159 offset:49152
	ds_read_b128 v[188:191], v159 offset:50176
	ds_read_b128 v[192:195], v159 offset:51200
	ds_read_b128 v[196:199], v159 offset:52224
	ds_read_b128 v[214:217], v159 offset:53248
	ds_read_b128 v[218:221], v159 offset:54272
	ds_read_b128 v[222:225], v159 offset:55296
	ds_read_b128 v[226:229], v159 offset:56320
	global_load_lds_dwordx4 v[200:201], off
	s_add_i32 m0, s28, 0x2000
	s_add_u32 s26, s26, 0xb0080
	v_lshl_add_u64 v[200:201], v[230:231], 0, s[46:47]
	s_addc_u32 s27, s27, 0
	s_add_i32 s28, s77, s70
	global_load_lds_dwordx4 v[200:201], off
	v_lshl_add_u64 v[200:201], s[26:27], 0, v[146:147]
	s_mov_b32 m0, s28
	s_nop 0
	global_load_lds_dwordx4 v[200:201], off
	v_lshl_add_u64 v[200:201], s[26:27], 0, v[148:149]
	s_add_i32 m0, s28, 0x2000
	s_nop 0
	global_load_lds_dwordx4 v[200:201], off
	v_lshl_add_u64 v[200:201], v[232:233], 0, s[46:47]
	s_mov_b32 m0, s75
	s_nop 0
	global_load_lds_dwordx4 v[200:201], off
	v_lshl_add_u64 v[200:201], v[234:235], 0, s[46:47]
	s_mov_b32 m0, s76
	s_nop 0
	global_load_lds_dwordx4 v[200:201], off
	s_waitcnt vmcnt(8)
	s_waitcnt lgkmcnt(0)
	s_barrier
	s_setprio 1
	s_waitcnt lgkmcnt(0)
	v_mfma_f32_16x16x32_bf16 v[64:67], v[132:135], v[184:187], v[64:67]
	v_mfma_f32_16x16x32_bf16 v[60:63], v[160:163], v[184:187], v[60:63]
	v_mfma_f32_16x16x32_bf16 v[48:51], v[132:135], v[192:195], v[48:51]
	v_mfma_f32_16x16x32_bf16 v[44:47], v[160:163], v[192:195], v[44:47]
	v_mfma_f32_16x16x32_bf16 v[32:35], v[132:135], v[214:217], v[32:35]
	v_mfma_f32_16x16x32_bf16 v[28:31], v[160:163], v[214:217], v[28:31]
	v_mfma_f32_16x16x32_bf16 v[16:19], v[132:135], v[222:225], v[16:19]
	v_mfma_f32_16x16x32_bf16 v[12:15], v[160:163], v[222:225], v[12:15]
	v_mfma_f32_16x16x32_bf16 v[64:67], v[140:143], v[188:191], v[64:67]
	v_mfma_f32_16x16x32_bf16 v[60:63], v[164:167], v[188:191], v[60:63]
	v_mfma_f32_16x16x32_bf16 v[48:51], v[140:143], v[196:199], v[48:51]
	v_mfma_f32_16x16x32_bf16 v[44:47], v[164:167], v[196:199], v[44:47]
	v_mfma_f32_16x16x32_bf16 v[32:35], v[140:143], v[218:221], v[32:35]
	v_mfma_f32_16x16x32_bf16 v[28:31], v[164:167], v[218:221], v[28:31]
	v_mfma_f32_16x16x32_bf16 v[16:19], v[140:143], v[226:229], v[16:19]
	v_mfma_f32_16x16x32_bf16 v[12:15], v[164:167], v[226:229], v[12:15]
	s_setprio 0
	s_setprio 1
	v_mfma_f32_16x16x32_bf16 v[56:59], v[168:171], v[184:187], v[56:59]
	v_mfma_f32_16x16x32_bf16 v[52:55], v[176:179], v[184:187], v[52:55]
	v_mfma_f32_16x16x32_bf16 v[40:43], v[168:171], v[192:195], v[40:43]
	v_mfma_f32_16x16x32_bf16 v[36:39], v[176:179], v[192:195], v[36:39]
	v_mfma_f32_16x16x32_bf16 v[24:27], v[168:171], v[214:217], v[24:27]
	v_mfma_f32_16x16x32_bf16 v[20:23], v[176:179], v[214:217], v[20:23]
	v_mfma_f32_16x16x32_bf16 v[8:11], v[168:171], v[222:225], v[8:11]
	v_mfma_f32_16x16x32_bf16 v[4:7], v[176:179], v[222:225], v[4:7]
	v_mfma_f32_16x16x32_bf16 v[56:59], v[172:175], v[188:191], v[56:59]
	v_mfma_f32_16x16x32_bf16 v[52:55], v[180:183], v[188:191], v[52:55]
	v_mfma_f32_16x16x32_bf16 v[40:43], v[172:175], v[196:199], v[40:43]
	v_mfma_f32_16x16x32_bf16 v[36:39], v[180:183], v[196:199], v[36:39]
	v_mfma_f32_16x16x32_bf16 v[24:27], v[172:175], v[218:221], v[24:27]
	v_mfma_f32_16x16x32_bf16 v[20:23], v[180:183], v[218:221], v[20:23]
	v_mfma_f32_16x16x32_bf16 v[8:11], v[172:175], v[226:229], v[8:11]
	v_mfma_f32_16x16x32_bf16 v[4:7], v[180:183], v[226:229], v[4:7]
	s_setprio 0
	s_barrier
	s_add_i32 s45, s45, 2
	s_add_u32 s24, s24, 0x100
	s_addc_u32 s25, s25, 0
	.p2alignl 6, 3212836864

; #define PG8_STAGE(bufoff, gbase, voff) do { _Pragma("unroll") for (int _i = 0; _i < 2; ++_i) \
;         __builtin_amdgcn_global_load_lds((const unsigned*)((const char*)(gbase) + (voff)[_i]), (LAS unsigned*)(lds + (bufoff) + ldsw + _i * 8192), 16, 0, 0); } while (0)
; #define PG8_LDA(dst, b, h) do { _Pragma("unroll") for (int m = 0; m < 4; ++m) _Pragma("unroll") for (int k = 0; k < 2; ++k) dst[m][k] = *(const LAS bf16x8*)(lds + PG8_SA(b, h) + aoff + m * 2048 + k * 1024); } while (0)
; #define PG8_WAIT_V(n) asm volatile("s_waitcnt vmcnt(" #n ")" ::: "memory")
; #define PG8_WAIT_L(n) asm volatile("s_waitcnt lgkmcnt(" #n ")" ::: "memory")
; template <class Epi>
; __device__ __forceinline__ void gemm_phase(LAS unsigned char* lds, const Gemm g, const int G, const int cidx, const Epi& E) {
;     ...
;     const char* cA = PG8_ABASE(cur); const char* cB = (const char*)g.Bt + (size_t)cur.pn * tstep;
;     PG8_STAGE(PG8_SB(0, 0), cB, voffB); PG8_STAGE(PG8_SB(0, 1), cB + hstep, voffB); PG8_STAGE(PG8_SA(0, 0), cA, voffA); PG8_STAGE(PG8_SA(0, 1), cA + hstep, voffA);
;     if (wr == 1) PG8_BAR;
;     PG8_WAIT_V(2); PG8_BAR;
;     PG8_STAGE(PG8_SB(1, 0), cB + kstep, voffB); PG8_STAGE(PG8_SA(1, 0), cA + kstep, voffA); PG8_STAGE(PG8_SB(1, 1), cB + hstep + kstep, voffB);
;     PG8_WAIT_V(6); PG8_BAR;
;     for (;;) {
;         const bool has_next = S.next(ui + 1, nxt);
;         const char* nA = has_next ? PG8_ABASE(nxt) : cA; const char* nB = has_next ? (const char*)g.Bt + (size_t)nxt.pn * tstep : cB;
;         for (int t = 0; t < nt; t += 2) {
;             const bool last = (t == nt - 2);
;             const char* a1 = cA + (size_t)(t + 1) * kstep;
;             const char* a2 = last ? nA : cA + (size_t)(t + 2) * kstep; const char* b2 = last ? nB : cB + (size_t)(t + 2) * kstep;
;             const char* a3 = a2 + kstep; const char* b3 = b2 + kstep;
;             PG8_LDB(B0, 0, 0); PG8_LDB(B1, 0, 1); PG8_SCHED; PG8_LDA(At, 0, 0); PG8_STAGE(PG8_SA(1, 1), a1 + hstep, voffA);
;             PG8_WAIT_V(8); PG8_WAIT_L(0); PG8_BAR; PG8_MMA(0, 0, At, B0); PG8_MMA(0, 1, At, B1); PG8_BAR; PG8_SCHED;
;             PG8_LDA(At, 0, 1); PG8_STAGE(PG8_SB(0, 0), b2, voffB); PG8_STAGE(PG8_SB(0, 1), b2 + hstep, voffB); PG8_STAGE(PG8_SA(0, 0), a2, voffA);
;             PG8_WAIT_V(8); PG8_WAIT_L(0); PG8_BAR; PG8_MMA(1, 0, At, B0); PG8_MMA(1, 1, At, B1); PG8_BAR; PG8_SCHED;
.LBB0_600:
	s_ashr_i32 s11, s10, 31
	v_cmp_lt_i64_e32 vcc, s[12:13], v[244:245]
	s_lshl_b64 s[12:13], s[10:11], 19
	s_add_u32 s12, s74, s12
	s_addc_u32 s13, s75, s13
	s_and_b64 s[14:15], vcc, exec
	s_cselect_b32 s11, s13, s25
	s_cselect_b32 s19, s12, s24
	s_ashr_i32 s9, s8, 31
	s_lshl_b64 s[14:15], s[8:9], 19
	s_add_u32 s14, s88, s14
	s_addc_u32 s15, s94, s15
	s_and_b64 s[26:27], vcc, exec
	s_cselect_b32 s9, s15, s21
	s_cselect_b32 s33, s14, s20
	s_add_u32 s42, s20, 0x100
	s_addc_u32 s44, s21, 0
	s_add_u32 s20, s24, 0x40080
	s_addc_u32 s21, s25, 0
	s_mov_b32 s45, -2
	s_add_u32 s24, s20, 0xfffc0080
	s_addc_u32 s25, s21, -1
	s_add_i32 s43, 0, 0x10000
	s_cmp_eq_u32 s45, 12
	s_cselect_b32 s27, s11, s25
	s_cselect_b32 s26, s19, s24
	v_add_u32_e32 v132, s43, v145
	s_cselect_b32 s25, s9, s44
	s_cselect_b32 s24, s33, s42
	s_add_i32 s68, 0, 0x14000
	ds_read_b128 v[158:161], v132
	ds_read_b128 v[164:167], v132 offset:1024
	ds_read_b128 v[168:171], v132 offset:2048
	ds_read_b128 v[172:175], v132 offset:3072
	v_add_u32_e32 v132, s68, v145
	ds_read_b128 v[176:179], v132
	ds_read_b128 v[180:183], v132 offset:1024
	ds_read_b128 v[184:187], v132 offset:2048
	ds_read_b128 v[188:191], v132 offset:3072
	v_lshl_add_u64 v[132:133], s[20:21], 0, v[156:157]
	s_add_i32 m0, s97, 0xc000
	ds_read_b128 v[192:195], v163
	ds_read_b128 v[196:199], v163 offset:1024
	ds_read_b128 v[214:217], v163 offset:2048
	ds_read_b128 v[218:221], v163 offset:3072
	ds_read_b128 v[222:225], v163 offset:4096
	ds_read_b128 v[226:229], v163 offset:5120
	ds_read_b128 v[230:233], v163 offset:6144
	ds_read_b128 v[234:237], v163 offset:7168
	global_load_lds_dwordx4 v[132:133], off
	v_lshl_add_u64 v[132:133], s[20:21], 0, v[154:155]
	s_add_i32 m0, s97, 0xe000
	s_nop 0
	global_load_lds_dwordx4 v[132:133], off
	s_waitcnt vmcnt(8)
	s_waitcnt lgkmcnt(0)
	s_barrier
	s_setprio 1
	s_waitcnt lgkmcnt(0)
	v_mfma_f32_16x16x32_bf16 v[128:131], v[158:161], v[192:195], 0
	v_mfma_f32_16x16x32_bf16 v[124:127], v[168:171], v[192:195], 0
	v_mfma_f32_16x16x32_bf16 v[120:123], v[158:161], v[214:217], 0
	v_mfma_f32_16x16x32_bf16 v[112:115], v[168:171], v[214:217], 0
	v_mfma_f32_16x16x32_bf16 v[104:107], v[158:161], v[222:225], 0
	v_mfma_f32_16x16x32_bf16 v[96:99], v[168:171], v[222:225], 0
	v_mfma_f32_16x16x32_bf16 v[88:91], v[158:161], v[230:233], 0
	v_mfma_f32_16x16x32_bf16 v[80:83], v[168:171], v[230:233], 0
	v_mfma_f32_16x16x32_bf16 v[128:131], v[164:167], v[196:199], v[128:131]
	v_mfma_f32_16x16x32_bf16 v[124:127], v[172:175], v[196:199], v[124:127]
	v_mfma_f32_16x16x32_bf16 v[120:123], v[164:167], v[218:221], v[120:123]
	v_mfma_f32_16x16x32_bf16 v[112:115], v[172:175], v[218:221], v[112:115]
	v_mfma_f32_16x16x32_bf16 v[104:107], v[164:167], v[226:229], v[104:107]
	v_mfma_f32_16x16x32_bf16 v[96:99], v[172:175], v[226:229], v[96:99]
	v_mfma_f32_16x16x32_bf16 v[88:91], v[164:167], v[234:237], v[88:91]
	v_mfma_f32_16x16x32_bf16 v[80:83], v[172:175], v[234:237], v[80:83]
	s_setprio 0
	s_setprio 1
	v_mfma_f32_16x16x32_bf16 v[116:119], v[176:179], v[192:195], 0
	v_mfma_f32_16x16x32_bf16 v[108:111], v[184:187], v[192:195], 0
	v_mfma_f32_16x16x32_bf16 v[100:103], v[176:179], v[214:217], 0
	v_mfma_f32_16x16x32_bf16 v[92:95], v[184:187], v[214:217], 0
	v_mfma_f32_16x16x32_bf16 v[84:87], v[176:179], v[222:225], 0
	v_mfma_f32_16x16x32_bf16 v[76:79], v[184:187], v[222:225], 0
	v_mfma_f32_16x16x32_bf16 v[72:75], v[176:179], v[230:233], 0
	v_mfma_f32_16x16x32_bf16 v[68:71], v[184:187], v[230:233], 0
	v_mfma_f32_16x16x32_bf16 v[116:119], v[180:183], v[196:199], v[116:119]
	v_mfma_f32_16x16x32_bf16 v[108:111], v[188:191], v[196:199], v[108:111]
	v_mfma_f32_16x16x32_bf16 v[100:103], v[180:183], v[218:221], v[100:103]
	v_mfma_f32_16x16x32_bf16 v[92:95], v[188:191], v[218:221], v[92:95]
	v_mfma_f32_16x16x32_bf16 v[84:87], v[180:183], v[226:229], v[84:87]
	v_mfma_f32_16x16x32_bf16 v[76:79], v[188:191], v[226:229], v[76:79]
	v_mfma_f32_16x16x32_bf16 v[72:75], v[180:183], v[234:237], v[72:75]
	v_mfma_f32_16x16x32_bf16 v[68:71], v[188:191], v[234:237], v[68:71]
	s_setprio 0
	s_barrier
	s_add_i32 s43, s43, s95
	v_lshl_add_u64 v[132:133], s[24:25], 0, v[148:149]
	s_mov_b32 m0, s43
	ds_read_b128 v[192:195], v163 offset:16384
	ds_read_b128 v[196:199], v163 offset:17408
	ds_read_b128 v[214:217], v163 offset:18432
	ds_read_b128 v[218:221], v163 offset:19456
	ds_read_b128 v[222:225], v163 offset:20480
	ds_read_b128 v[226:229], v163 offset:21504
	ds_read_b128 v[230:233], v163 offset:22528
	ds_read_b128 v[234:237], v163 offset:23552
	global_load_lds_dwordx4 v[132:133], off
	s_add_i32 m0, s43, 0x2000
	s_add_u32 s86, s24, 0x40000
	v_lshl_add_u64 v[134:135], s[24:25], 0, v[0:1]
	s_addc_u32 s87, s25, 0
	s_add_i32 s43, s68, s95
	global_load_lds_dwordx4 v[134:135], off
	v_lshl_add_u64 v[140:141], s[86:87], 0, v[148:149]
	s_mov_b32 m0, s43
	v_lshl_add_u64 v[142:143], s[26:27], 0, v[146:147]
	global_load_lds_dwordx4 v[140:141], off
	v_lshl_add_u64 v[140:141], s[86:87], 0, v[0:1]
	s_add_i32 m0, s43, 0x2000
	s_nop 0
	global_load_lds_dwordx4 v[140:141], off
	v_lshl_add_u64 v[140:141], s[26:27], 0, v[150:151]
	s_mov_b32 m0, s97
	s_nop 0
	global_load_lds_dwordx4 v[140:141], off
	s_mov_b32 m0, s22
	s_nop 0
	global_load_lds_dwordx4 v[142:143], off
	s_waitcnt vmcnt(8)
	s_waitcnt lgkmcnt(0)
	s_barrier
; #define PG8_STAGE(bufoff, gbase, voff) do { _Pragma("unroll") for (int _i = 0; _i < 2; ++_i) \
;         __builtin_amdgcn_global_load_lds((const unsigned*)((const char*)(gbase) + (voff)[_i]), (LAS unsigned*)(lds + (bufoff) + ldsw + _i * 8192), 16, 0, 0); } while (0)
; #define PG8_LDA(dst, b, h) do { _Pragma("unroll") for (int m = 0; m < 4; ++m) _Pragma("unroll") for (int k = 0; k < 2; ++k) dst[m][k] = *(const LAS bf16x8*)(lds + PG8_SA(b, h) + aoff + m * 2048 + k * 1024); } while (0)
; #define PG8_LDB(dst, b, h) do { _Pragma("unroll") for (int n = 0; n < 2; ++n) _Pragma("unroll") for (int k = 0; k < 2; ++k) dst[n][k] = *(const LAS bf16x8*)(lds + PG8_SB(b, h) + boff + n * 2048 + k * 1024); } while (0)
; #define PG8_MMA(ai, bj, At, Bt) do { __builtin_amdgcn_s_setprio(1); _Pragma("unroll") for (int m = 0; m < 4; ++m) _Pragma("unroll") for (int n = 0; n < 2; ++n) _Pragma("unroll") for (int k = 0; k < 2; ++k) \
;         acc[ai][bj][m][n] = __builtin_amdgcn_mfma_f32_16x16x32_bf16(Bt[n][k], At[m][k], acc[ai][bj][m][n], 0, 0, 0); __builtin_amdgcn_s_setprio(0); } while (0)
; #define PG8_WAIT_V(n) asm volatile("s_waitcnt vmcnt(" #n ")" ::: "memory")
; #define PG8_WAIT_L(n) asm volatile("s_waitcnt lgkmcnt(" #n ")" ::: "memory")
; #define PG8_BAR __builtin_amdgcn_s_barrier()
; #define PG8_SCHED __builtin_amdgcn_sched_barrier(0)
; template <class Epi>
; __device__ __forceinline__ void gemm_phase(LAS unsigned char* lds, const Gemm g, const int G, const int cidx, const Epi& E) {
;     ...
;             PG8_WAIT_V(8); PG8_WAIT_L(0); PG8_BAR; PG8_MMA(1, 0, At, B0); PG8_MMA(1, 1, At, B1); PG8_BAR; PG8_SCHED;
;             PG8_LDB(B0, 1, 0); PG8_LDB(B1, 1, 1); PG8_SCHED; PG8_LDA(At, 1, 0); PG8_STAGE(PG8_SA(0, 1), a2 + hstep, voffA);
;             PG8_WAIT_V(8); PG8_WAIT_L(0); PG8_BAR; PG8_MMA(0, 0, At, B0); PG8_MMA(0, 1, At, B1); PG8_BAR; PG8_SCHED;
	s_setprio 1
	s_waitcnt lgkmcnt(0)
	v_mfma_f32_16x16x32_bf16 v[64:67], v[158:161], v[192:195], 0
	v_mfma_f32_16x16x32_bf16 v[60:63], v[168:171], v[192:195], 0
	v_mfma_f32_16x16x32_bf16 v[56:59], v[158:161], v[214:217], 0
	v_mfma_f32_16x16x32_bf16 v[48:51], v[168:171], v[214:217], 0
	v_mfma_f32_16x16x32_bf16 v[40:43], v[158:161], v[222:225], 0
	v_mfma_f32_16x16x32_bf16 v[32:35], v[168:171], v[222:225], 0
	v_mfma_f32_16x16x32_bf16 v[24:27], v[158:161], v[230:233], 0
	v_mfma_f32_16x16x32_bf16 v[16:19], v[168:171], v[230:233], 0
	v_mfma_f32_16x16x32_bf16 v[64:67], v[164:167], v[196:199], v[64:67]
	v_mfma_f32_16x16x32_bf16 v[60:63], v[172:175], v[196:199], v[60:63]
	v_mfma_f32_16x16x32_bf16 v[56:59], v[164:167], v[218:221], v[56:59]
	v_mfma_f32_16x16x32_bf16 v[48:51], v[172:175], v[218:221], v[48:51]
	v_mfma_f32_16x16x32_bf16 v[40:43], v[164:167], v[226:229], v[40:43]
	v_mfma_f32_16x16x32_bf16 v[32:35], v[172:175], v[226:229], v[32:35]
	v_mfma_f32_16x16x32_bf16 v[24:27], v[164:167], v[234:237], v[24:27]
	v_mfma_f32_16x16x32_bf16 v[16:19], v[172:175], v[234:237], v[16:19]
	s_setprio 0
	s_setprio 1
	v_mfma_f32_16x16x32_bf16 v[52:55], v[176:179], v[192:195], 0
	v_mfma_f32_16x16x32_bf16 v[44:47], v[184:187], v[192:195], 0
	v_mfma_f32_16x16x32_bf16 v[36:39], v[176:179], v[214:217], 0
	v_mfma_f32_16x16x32_bf16 v[28:31], v[184:187], v[214:217], 0
	v_mfma_f32_16x16x32_bf16 v[20:23], v[176:179], v[222:225], 0
	v_mfma_f32_16x16x32_bf16 v[12:15], v[184:187], v[222:225], 0
	v_mfma_f32_16x16x32_bf16 v[8:11], v[176:179], v[230:233], 0
	v_mfma_f32_16x16x32_bf16 v[4:7], v[184:187], v[230:233], 0
	v_mfma_f32_16x16x32_bf16 v[52:55], v[180:183], v[196:199], v[52:55]
	v_mfma_f32_16x16x32_bf16 v[44:47], v[188:191], v[196:199], v[44:47]
	v_mfma_f32_16x16x32_bf16 v[36:39], v[180:183], v[218:221], v[36:39]
	v_mfma_f32_16x16x32_bf16 v[28:31], v[188:191], v[218:221], v[28:31]
	v_mfma_f32_16x16x32_bf16 v[20:23], v[180:183], v[226:229], v[20:23]
	v_mfma_f32_16x16x32_bf16 v[12:15], v[188:191], v[226:229], v[12:15]
	v_mfma_f32_16x16x32_bf16 v[8:11], v[180:183], v[234:237], v[8:11]
	v_mfma_f32_16x16x32_bf16 v[4:7], v[188:191], v[234:237], v[4:7]
	s_setprio 0
	s_barrier
	s_add_i32 s43, 0, 0x18000
	s_add_i32 s68, 0, 0x1c000
	v_add_u32_e32 v172, s43, v145
	v_add_u32_e32 v188, s68, v145
	ds_read_b128 v[158:161], v172
	ds_read_b128 v[164:167], v172 offset:1024
	ds_read_b128 v[168:171], v172 offset:2048
	ds_read_b128 v[172:175], v172 offset:3072
	ds_read_b128 v[176:179], v188
	ds_read_b128 v[180:183], v188 offset:1024
	ds_read_b128 v[184:187], v188 offset:2048
	ds_read_b128 v[188:191], v188 offset:3072
	s_add_u32 s26, s26, 0x40000
	s_addc_u32 s27, s27, 0
	s_mov_b32 m0, s16
	v_lshl_add_u64 v[200:201], s[26:27], 0, v[150:151]
	ds_read_b128 v[192:195], v163 offset:32768
	ds_read_b128 v[196:199], v163 offset:33792
	ds_read_b128 v[214:217], v163 offset:34816
	ds_read_b128 v[218:221], v163 offset:35840
	ds_read_b128 v[222:225], v163 offset:36864
	ds_read_b128 v[226:229], v163 offset:37888
	ds_read_b128 v[230:233], v163 offset:38912
	ds_read_b128 v[234:237], v163 offset:39936
	global_load_lds_dwordx4 v[200:201], off
	v_lshl_add_u64 v[200:201], s[26:27], 0, v[146:147]
	s_mov_b32 m0, s17
	s_nop 0
	global_load_lds_dwordx4 v[200:201], off
	s_waitcnt vmcnt(8)
	s_waitcnt lgkmcnt(0)
	s_barrier
	s_setprio 1
	s_waitcnt lgkmcnt(0)
	v_mfma_f32_16x16x32_bf16 v[128:131], v[158:161], v[192:195], v[128:131]
	v_mfma_f32_16x16x32_bf16 v[124:127], v[168:171], v[192:195], v[124:127]
	v_mfma_f32_16x16x32_bf16 v[120:123], v[158:161], v[214:217], v[120:123]
	v_mfma_f32_16x16x32_bf16 v[112:115], v[168:171], v[214:217], v[112:115]
	v_mfma_f32_16x16x32_bf16 v[104:107], v[158:161], v[222:225], v[104:107]
	v_mfma_f32_16x16x32_bf16 v[96:99], v[168:171], v[222:225], v[96:99]
	v_mfma_f32_16x16x32_bf16 v[88:91], v[158:161], v[230:233], v[88:91]
	v_mfma_f32_16x16x32_bf16 v[80:83], v[168:171], v[230:233], v[80:83]
	v_mfma_f32_16x16x32_bf16 v[128:131], v[164:167], v[196:199], v[128:131]
	v_mfma_f32_16x16x32_bf16 v[124:127], v[172:175], v[196:199], v[124:127]
	v_mfma_f32_16x16x32_bf16 v[120:123], v[164:167], v[218:221], v[120:123]
	v_mfma_f32_16x16x32_bf16 v[112:115], v[172:175], v[218:221], v[112:115]
	v_mfma_f32_16x16x32_bf16 v[104:107], v[164:167], v[226:229], v[104:107]
	v_mfma_f32_16x16x32_bf16 v[96:99], v[172:175], v[226:229], v[96:99]
	v_mfma_f32_16x16x32_bf16 v[88:91], v[164:167], v[234:237], v[88:91]
	v_mfma_f32_16x16x32_bf16 v[80:83], v[172:175], v[234:237], v[80:83]
	s_setprio 0
	s_setprio 1
	v_mfma_f32_16x16x32_bf16 v[116:119], v[176:179], v[192:195], v[116:119]
	v_mfma_f32_16x16x32_bf16 v[108:111], v[184:187], v[192:195], v[108:111]
	v_mfma_f32_16x16x32_bf16 v[100:103], v[176:179], v[214:217], v[100:103]
	v_mfma_f32_16x16x32_bf16 v[92:95], v[184:187], v[214:217], v[92:95]
	v_mfma_f32_16x16x32_bf16 v[84:87], v[176:179], v[222:225], v[84:87]
	v_mfma_f32_16x16x32_bf16 v[76:79], v[184:187], v[222:225], v[76:79]
	v_mfma_f32_16x16x32_bf16 v[72:75], v[176:179], v[230:233], v[72:75]
	v_mfma_f32_16x16x32_bf16 v[68:71], v[184:187], v[230:233], v[68:71]
	v_mfma_f32_16x16x32_bf16 v[116:119], v[180:183], v[196:199], v[116:119]
	v_mfma_f32_16x16x32_bf16 v[108:111], v[188:191], v[196:199], v[108:111]
	v_mfma_f32_16x16x32_bf16 v[100:103], v[180:183], v[218:221], v[100:103]
	v_mfma_f32_16x16x32_bf16 v[92:95], v[188:191], v[218:221], v[92:95]
	v_mfma_f32_16x16x32_bf16 v[84:87], v[180:183], v[226:229], v[84:87]
	v_mfma_f32_16x16x32_bf16 v[76:79], v[188:191], v[226:229], v[76:79]
	v_mfma_f32_16x16x32_bf16 v[72:75], v[180:183], v[234:237], v[72:75]
	v_mfma_f32_16x16x32_bf16 v[68:71], v[188:191], v[234:237], v[68:71]
	s_setprio 0
	s_barrier
; #define PG8_STAGE(bufoff, gbase, voff) do { _Pragma("unroll") for (int _i = 0; _i < 2; ++_i) \
;         __builtin_amdgcn_global_load_lds((const unsigned*)((const char*)(gbase) + (voff)[_i]), (LAS unsigned*)(lds + (bufoff) + ldsw + _i * 8192), 16, 0, 0); } while (0)
; #define PG8_LDA(dst, b, h) do { _Pragma("unroll") for (int m = 0; m < 4; ++m) _Pragma("unroll") for (int k = 0; k < 2; ++k) dst[m][k] = *(const LAS bf16x8*)(lds + PG8_SA(b, h) + aoff + m * 2048 + k * 1024); } while (0)
; #define PG8_MMA(ai, bj, At, Bt) do { __builtin_amdgcn_s_setprio(1); _Pragma("unroll") for (int m = 0; m < 4; ++m) _Pragma("unroll") for (int n = 0; n < 2; ++n) _Pragma("unroll") for (int k = 0; k < 2; ++k) \
;         acc[ai][bj][m][n] = __builtin_amdgcn_mfma_f32_16x16x32_bf16(Bt[n][k], At[m][k], acc[ai][bj][m][n], 0, 0, 0); __builtin_amdgcn_s_setprio(0); } while (0)
; #define PG8_WAIT_V(n) asm volatile("s_waitcnt vmcnt(" #n ")" ::: "memory")
; #define PG8_WAIT_L(n) asm volatile("s_waitcnt lgkmcnt(" #n ")" ::: "memory")
; #define PG8_BAR __builtin_amdgcn_s_barrier()
; #define PG8_SCHED __builtin_amdgcn_sched_barrier(0)
; template <class Epi>
; __device__ __forceinline__ void gemm_phase(LAS unsigned char* lds, const Gemm g, const int G, const int cidx, const Epi& E) {
;     ...
;             PG8_LDA(At, 1, 1); PG8_STAGE(PG8_SB(1, 0), b3, voffB); PG8_STAGE(PG8_SB(1, 1), b3 + hstep, voffB); PG8_STAGE(PG8_SA(1, 0), a3, voffA);
;             PG8_WAIT_V(8); PG8_WAIT_L(0); PG8_BAR; PG8_MMA(1, 0, At, B0); PG8_MMA(1, 1, At, B1); PG8_BAR; PG8_SCHED;
;         }
	s_add_i32 s26, s43, s95
	v_lshl_add_u64 v[132:133], v[132:133], 0, s[46:47]
	s_mov_b32 m0, s26
	ds_read_b128 v[192:195], v163 offset:49152
	ds_read_b128 v[196:199], v163 offset:50176
	ds_read_b128 v[214:217], v163 offset:51200
	ds_read_b128 v[218:221], v163 offset:52224
	ds_read_b128 v[222:225], v163 offset:53248
	ds_read_b128 v[226:229], v163 offset:54272
	ds_read_b128 v[230:233], v163 offset:55296
	ds_read_b128 v[234:237], v163 offset:56320
	global_load_lds_dwordx4 v[132:133], off
	s_add_i32 m0, s26, 0x2000
	s_add_u32 s24, s24, 0x40080
	v_lshl_add_u64 v[132:133], v[134:135], 0, s[46:47]
	s_addc_u32 s25, s25, 0
	s_add_i32 s26, s68, s95
	global_load_lds_dwordx4 v[132:133], off
	v_lshl_add_u64 v[132:133], s[24:25], 0, v[148:149]
	s_mov_b32 m0, s26
	s_nop 0
	global_load_lds_dwordx4 v[132:133], off
	v_lshl_add_u64 v[132:133], s[24:25], 0, v[0:1]
	s_add_i32 m0, s26, 0x2000
	s_nop 0
	global_load_lds_dwordx4 v[132:133], off
	v_lshl_add_u64 v[132:133], v[140:141], 0, s[46:47]
	s_mov_b32 m0, s84
	s_nop 0
	global_load_lds_dwordx4 v[132:133], off
	v_lshl_add_u64 v[132:133], v[142:143], 0, s[46:47]
	s_mov_b32 m0, s76
	s_nop 0
	global_load_lds_dwordx4 v[132:133], off
	s_waitcnt vmcnt(8)
	s_waitcnt lgkmcnt(0)
	s_barrier
	s_setprio 1
	s_waitcnt lgkmcnt(0)
	v_mfma_f32_16x16x32_bf16 v[64:67], v[158:161], v[192:195], v[64:67]
	v_mfma_f32_16x16x32_bf16 v[60:63], v[168:171], v[192:195], v[60:63]
	v_mfma_f32_16x16x32_bf16 v[56:59], v[158:161], v[214:217], v[56:59]
	v_mfma_f32_16x16x32_bf16 v[48:51], v[168:171], v[214:217], v[48:51]
	v_mfma_f32_16x16x32_bf16 v[40:43], v[158:161], v[222:225], v[40:43]
	v_mfma_f32_16x16x32_bf16 v[32:35], v[168:171], v[222:225], v[32:35]
	v_mfma_f32_16x16x32_bf16 v[24:27], v[158:161], v[230:233], v[24:27]
	v_mfma_f32_16x16x32_bf16 v[16:19], v[168:171], v[230:233], v[16:19]
	v_mfma_f32_16x16x32_bf16 v[64:67], v[164:167], v[196:199], v[64:67]
	v_mfma_f32_16x16x32_bf16 v[60:63], v[172:175], v[196:199], v[60:63]
	v_mfma_f32_16x16x32_bf16 v[56:59], v[164:167], v[218:221], v[56:59]
	v_mfma_f32_16x16x32_bf16 v[48:51], v[172:175], v[218:221], v[48:51]
	v_mfma_f32_16x16x32_bf16 v[40:43], v[164:167], v[226:229], v[40:43]
	v_mfma_f32_16x16x32_bf16 v[32:35], v[172:175], v[226:229], v[32:35]
	v_mfma_f32_16x16x32_bf16 v[24:27], v[164:167], v[234:237], v[24:27]
	v_mfma_f32_16x16x32_bf16 v[16:19], v[172:175], v[234:237], v[16:19]
	s_setprio 0
	s_setprio 1
	v_mfma_f32_16x16x32_bf16 v[52:55], v[176:179], v[192:195], v[52:55]
	v_mfma_f32_16x16x32_bf16 v[44:47], v[184:187], v[192:195], v[44:47]
	v_mfma_f32_16x16x32_bf16 v[36:39], v[176:179], v[214:217], v[36:39]
	v_mfma_f32_16x16x32_bf16 v[28:31], v[184:187], v[214:217], v[28:31]
	v_mfma_f32_16x16x32_bf16 v[20:23], v[176:179], v[222:225], v[20:23]
	v_mfma_f32_16x16x32_bf16 v[12:15], v[184:187], v[222:225], v[12:15]
	v_mfma_f32_16x16x32_bf16 v[8:11], v[176:179], v[230:233], v[8:11]
	v_mfma_f32_16x16x32_bf16 v[4:7], v[184:187], v[230:233], v[4:7]
	v_mfma_f32_16x16x32_bf16 v[52:55], v[180:183], v[196:199], v[52:55]
	v_mfma_f32_16x16x32_bf16 v[44:47], v[188:191], v[196:199], v[44:47]
	v_mfma_f32_16x16x32_bf16 v[36:39], v[180:183], v[218:221], v[36:39]
	v_mfma_f32_16x16x32_bf16 v[28:31], v[188:191], v[218:221], v[28:31]
	v_mfma_f32_16x16x32_bf16 v[20:23], v[180:183], v[226:229], v[20:23]
	v_mfma_f32_16x16x32_bf16 v[12:15], v[188:191], v[226:229], v[12:15]
	v_mfma_f32_16x16x32_bf16 v[8:11], v[180:183], v[234:237], v[8:11]
	v_mfma_f32_16x16x32_bf16 v[4:7], v[188:191], v[234:237], v[4:7]
	s_setprio 0
	s_barrier
	s_add_i32 s45, s45, 2
	s_add_u32 s42, s42, 0x100
	s_addc_u32 s44, s44, 0
	s_add_u32 s20, s20, 0x100
	s_addc_u32 s21, s21, 0
	.p2alignl 6, 3212836864
